# GEMM K-loops: drop mid-block setprio 0/1 pair and the post-barrier repeat of lgkmcnt(0)
# speedup vs baseline: 1.0098x; 1.0098x over previous
.LBB0_92:
	s_add_i32 s21, s20, 2
	s_add_u32 s12, s28, 0x80
	s_addc_u32 s13, s29, 0
	s_add_i32 s36, 0, 0x10000
	s_cmp_eq_u32 s1, s20
	s_cselect_b32 s59, s5, s13
	s_cselect_b32 s58, s4, s12
	s_cselect_b32 s13, s57, s19
	s_cselect_b32 s12, s56, s18
	s_add_i32 s20, 0, 0x14000
	v_add_u32_e32 v60, s36, v175
	v_add_u32_e32 v76, s20, v175
	ds_read_b128 v[48:51], v60
	ds_read_b128 v[52:55], v60 offset:1024
	ds_read_b128 v[56:59], v60 offset:2048
	ds_read_b128 v[60:63], v60 offset:3072
	ds_read_b128 v[64:67], v76
	ds_read_b128 v[68:71], v76 offset:1024
	ds_read_b128 v[72:75], v76 offset:2048
	ds_read_b128 v[76:79], v76 offset:3072
	v_lshl_add_u64 v[190:191], s[28:29], 0, v[166:167]
	s_add_i32 m0, s72, 0xc000
	ds_read_b128 v[170:173], v177
	ds_read_b128 v[178:181], v177 offset:1024
	ds_read_b128 v[182:185], v177 offset:2048
	ds_read_b128 v[186:189], v177 offset:3072
	ds_read_b128 v[194:197], v177 offset:4096
	ds_read_b128 v[198:201], v177 offset:5120
	ds_read_b128 v[202:205], v177 offset:6144
	ds_read_b128 v[212:215], v177 offset:7168
	global_load_lds_dwordx4 v[190:191], off
	v_lshl_add_u64 v[190:191], s[28:29], 0, v[168:169]
	s_add_i32 m0, s72, 0xe000
	s_nop 0
	global_load_lds_dwordx4 v[190:191], off
	s_waitcnt vmcnt(8)
	s_waitcnt lgkmcnt(0)
	s_barrier
	s_setprio 1
	v_mfma_f32_16x16x32_bf16 v[156:159], v[48:51], v[170:173], v[156:159]
	v_mfma_f32_16x16x32_bf16 v[152:155], v[56:59], v[170:173], v[152:155]
	v_mfma_f32_16x16x32_bf16 v[140:143], v[48:51], v[182:185], v[140:143]
	v_mfma_f32_16x16x32_bf16 v[136:139], v[56:59], v[182:185], v[136:139]
	v_mfma_f32_16x16x32_bf16 v[124:127], v[48:51], v[194:197], v[124:127]
	v_mfma_f32_16x16x32_bf16 v[120:123], v[56:59], v[194:197], v[120:123]
	v_mfma_f32_16x16x32_bf16 v[108:111], v[48:51], v[202:205], v[108:111]
	v_mfma_f32_16x16x32_bf16 v[104:107], v[56:59], v[202:205], v[104:107]
	v_mfma_f32_16x16x32_bf16 v[156:159], v[52:55], v[178:181], v[156:159]
	v_mfma_f32_16x16x32_bf16 v[152:155], v[60:63], v[178:181], v[152:155]
	v_mfma_f32_16x16x32_bf16 v[140:143], v[52:55], v[186:189], v[140:143]
	v_mfma_f32_16x16x32_bf16 v[136:139], v[60:63], v[186:189], v[136:139]
	v_mfma_f32_16x16x32_bf16 v[124:127], v[52:55], v[198:201], v[124:127]
	v_mfma_f32_16x16x32_bf16 v[120:123], v[60:63], v[198:201], v[120:123]
	v_mfma_f32_16x16x32_bf16 v[108:111], v[52:55], v[212:215], v[108:111]
	v_mfma_f32_16x16x32_bf16 v[104:107], v[60:63], v[212:215], v[104:107]
	v_mfma_f32_16x16x32_bf16 v[148:151], v[64:67], v[170:173], v[148:151]
	v_mfma_f32_16x16x32_bf16 v[144:147], v[72:75], v[170:173], v[144:147]
	v_mfma_f32_16x16x32_bf16 v[132:135], v[64:67], v[182:185], v[132:135]
	v_mfma_f32_16x16x32_bf16 v[128:131], v[72:75], v[182:185], v[128:131]
	v_mfma_f32_16x16x32_bf16 v[116:119], v[64:67], v[194:197], v[116:119]
	v_mfma_f32_16x16x32_bf16 v[112:115], v[72:75], v[194:197], v[112:115]
	v_mfma_f32_16x16x32_bf16 v[100:103], v[64:67], v[202:205], v[100:103]
	v_mfma_f32_16x16x32_bf16 v[96:99], v[72:75], v[202:205], v[96:99]
	v_mfma_f32_16x16x32_bf16 v[148:151], v[68:71], v[178:181], v[148:151]
	v_mfma_f32_16x16x32_bf16 v[144:147], v[76:79], v[178:181], v[144:147]
	v_mfma_f32_16x16x32_bf16 v[132:135], v[68:71], v[186:189], v[132:135]
	v_mfma_f32_16x16x32_bf16 v[128:131], v[76:79], v[186:189], v[128:131]
	v_mfma_f32_16x16x32_bf16 v[116:119], v[68:71], v[198:201], v[116:119]
	v_mfma_f32_16x16x32_bf16 v[112:115], v[76:79], v[198:201], v[112:115]
	v_mfma_f32_16x16x32_bf16 v[100:103], v[68:71], v[212:215], v[100:103]
	v_mfma_f32_16x16x32_bf16 v[96:99], v[76:79], v[212:215], v[96:99]
	s_setprio 0
	s_barrier
	s_add_i32 s36, s36, s9
	v_lshl_add_u64 v[190:191], s[12:13], 0, v[192:193]
	s_mov_b32 m0, s36
	ds_read_b128 v[170:173], v177 offset:16384
	ds_read_b128 v[178:181], v177 offset:17408
	ds_read_b128 v[182:185], v177 offset:18432
	ds_read_b128 v[186:189], v177 offset:19456
	ds_read_b128 v[194:197], v177 offset:20480
	ds_read_b128 v[198:201], v177 offset:21504
	ds_read_b128 v[202:205], v177 offset:22528
	ds_read_b128 v[212:215], v177 offset:23552
	global_load_lds_dwordx4 v[190:191], off
	s_add_i32 m0, s36, 0x2000
	v_lshl_add_u64 v[206:207], s[12:13], 0, v[160:161]
	s_add_u32 s12, s12, s10
	s_addc_u32 s13, s13, 0
	s_add_i32 s20, s20, s9
	global_load_lds_dwordx4 v[206:207], off
	v_lshl_add_u64 v[208:209], s[12:13], 0, v[192:193]
	s_mov_b32 m0, s20
	v_lshl_add_u64 v[232:233], s[12:13], 0, v[160:161]
	global_load_lds_dwordx4 v[208:209], off
	s_add_i32 m0, s20, 0x2000
	v_lshl_add_u64 v[246:247], s[58:59], 0, v[164:165]
	global_load_lds_dwordx4 v[232:233], off
	s_mov_b32 m0, s72
	v_lshl_add_u64 v[248:249], s[58:59], 0, v[162:163]
	global_load_lds_dwordx4 v[246:247], off
	s_mov_b32 m0, s73
	s_nop 0
	global_load_lds_dwordx4 v[248:249], off
	s_waitcnt vmcnt(8)
	s_waitcnt lgkmcnt(0)
	s_barrier
	s_setprio 1
	v_mfma_f32_16x16x32_bf16 v[92:95], v[48:51], v[170:173], v[92:95]
	v_mfma_f32_16x16x32_bf16 v[88:91], v[56:59], v[170:173], v[88:91]
	v_mfma_f32_16x16x32_bf16 v[44:47], v[48:51], v[182:185], v[44:47]
	v_mfma_f32_16x16x32_bf16 v[40:43], v[56:59], v[182:185], v[40:43]
	v_mfma_f32_16x16x32_bf16 v[28:31], v[48:51], v[194:197], v[28:31]
	v_mfma_f32_16x16x32_bf16 v[24:27], v[56:59], v[194:197], v[24:27]
	v_mfma_f32_16x16x32_bf16 v[12:15], v[48:51], v[202:205], v[12:15]
	v_mfma_f32_16x16x32_bf16 v[8:11], v[56:59], v[202:205], v[8:11]
	v_mfma_f32_16x16x32_bf16 v[92:95], v[52:55], v[178:181], v[92:95]
	v_mfma_f32_16x16x32_bf16 v[88:91], v[60:63], v[178:181], v[88:91]
	v_mfma_f32_16x16x32_bf16 v[44:47], v[52:55], v[186:189], v[44:47]
	v_mfma_f32_16x16x32_bf16 v[40:43], v[60:63], v[186:189], v[40:43]
	v_mfma_f32_16x16x32_bf16 v[28:31], v[52:55], v[198:201], v[28:31]
	v_mfma_f32_16x16x32_bf16 v[24:27], v[60:63], v[198:201], v[24:27]
	v_mfma_f32_16x16x32_bf16 v[12:15], v[52:55], v[212:215], v[12:15]
	v_mfma_f32_16x16x32_bf16 v[8:11], v[60:63], v[212:215], v[8:11]
	v_mfma_f32_16x16x32_bf16 v[36:39], v[64:67], v[182:185], v[36:39]
	v_mfma_f32_16x16x32_bf16 v[32:35], v[72:75], v[182:185], v[32:35]
	v_mfma_f32_16x16x32_bf16 v[20:23], v[64:67], v[194:197], v[20:23]
	v_mfma_f32_16x16x32_bf16 v[16:19], v[72:75], v[194:197], v[16:19]
	v_mfma_f32_16x16x32_bf16 v[4:7], v[64:67], v[202:205], v[4:7]
	v_mfma_f32_16x16x32_bf16 v[0:3], v[72:75], v[202:205], v[0:3]
	v_mfma_f32_16x16x32_bf16 v[48:51], v[64:67], v[170:173], v[84:87]
	v_mfma_f32_16x16x32_bf16 v[52:55], v[72:75], v[170:173], v[80:83]
	v_mfma_f32_16x16x32_bf16 v[36:39], v[68:71], v[186:189], v[36:39]
	v_mfma_f32_16x16x32_bf16 v[32:35], v[76:79], v[186:189], v[32:35]
	v_mfma_f32_16x16x32_bf16 v[20:23], v[68:71], v[198:201], v[20:23]
	v_mfma_f32_16x16x32_bf16 v[16:19], v[76:79], v[198:201], v[16:19]
	v_mfma_f32_16x16x32_bf16 v[4:7], v[68:71], v[212:215], v[4:7]
	v_mfma_f32_16x16x32_bf16 v[0:3], v[76:79], v[212:215], v[0:3]
	v_mfma_f32_16x16x32_bf16 v[48:51], v[68:71], v[178:181], v[48:51]
	v_mfma_f32_16x16x32_bf16 v[52:55], v[76:79], v[178:181], v[52:55]
	s_setprio 0
	s_barrier
	s_add_i32 s20, 0, 0x18000
	s_add_i32 s36, 0, 0x1c000
	v_add_u32_e32 v68, s20, v175
	v_add_u32_e32 v80, s36, v175
	ds_read_b128 v[56:59], v68
	ds_read_b128 v[60:63], v68 offset:1024
	ds_read_b128 v[64:67], v68 offset:2048
	ds_read_b128 v[68:71], v68 offset:3072
	ds_read_b128 v[72:75], v80
	ds_read_b128 v[76:79], v80 offset:1024
	ds_read_b128 v[170:173], v80 offset:2048
	ds_read_b128 v[178:181], v80 offset:3072
	s_add_u32 s12, s58, s30
	s_addc_u32 s13, s59, 0
	s_mov_b32 m0, s74
	v_lshl_add_u64 v[242:243], s[12:13], 0, v[164:165]
	ds_read_b128 v[80:83], v177 offset:32768
	ds_read_b128 v[84:87], v177 offset:33792
	ds_read_b128 v[182:185], v177 offset:34816
	ds_read_b128 v[186:189], v177 offset:35840
	ds_read_b128 v[194:197], v177 offset:36864
	ds_read_b128 v[198:201], v177 offset:37888
	ds_read_b128 v[202:205], v177 offset:38912
	ds_read_b128 v[212:215], v177 offset:39936
	global_load_lds_dwordx4 v[242:243], off
	v_lshl_add_u64 v[242:243], s[12:13], 0, v[162:163]
	s_mov_b32 m0, s75
	s_nop 0
	global_load_lds_dwordx4 v[242:243], off
	s_waitcnt vmcnt(8)
	s_waitcnt lgkmcnt(0)
	s_barrier
	s_setprio 1
	v_mfma_f32_16x16x32_bf16 v[156:159], v[56:59], v[80:83], v[156:159]
	v_mfma_f32_16x16x32_bf16 v[152:155], v[64:67], v[80:83], v[152:155]
	v_mfma_f32_16x16x32_bf16 v[140:143], v[56:59], v[182:185], v[140:143]
	v_mfma_f32_16x16x32_bf16 v[136:139], v[64:67], v[182:185], v[136:139]
	v_mfma_f32_16x16x32_bf16 v[124:127], v[56:59], v[194:197], v[124:127]
	v_mfma_f32_16x16x32_bf16 v[120:123], v[64:67], v[194:197], v[120:123]
	v_mfma_f32_16x16x32_bf16 v[108:111], v[56:59], v[202:205], v[108:111]
	v_mfma_f32_16x16x32_bf16 v[104:107], v[64:67], v[202:205], v[104:107]
	v_mfma_f32_16x16x32_bf16 v[156:159], v[60:63], v[84:87], v[156:159]
	v_mfma_f32_16x16x32_bf16 v[152:155], v[68:71], v[84:87], v[152:155]
	v_mfma_f32_16x16x32_bf16 v[140:143], v[60:63], v[186:189], v[140:143]
	v_mfma_f32_16x16x32_bf16 v[136:139], v[68:71], v[186:189], v[136:139]
	v_mfma_f32_16x16x32_bf16 v[124:127], v[60:63], v[198:201], v[124:127]
	v_mfma_f32_16x16x32_bf16 v[120:123], v[68:71], v[198:201], v[120:123]
	v_mfma_f32_16x16x32_bf16 v[108:111], v[60:63], v[212:215], v[108:111]
	v_mfma_f32_16x16x32_bf16 v[104:107], v[68:71], v[212:215], v[104:107]
	v_mfma_f32_16x16x32_bf16 v[148:151], v[72:75], v[80:83], v[148:151]
	v_mfma_f32_16x16x32_bf16 v[80:83], v[170:173], v[80:83], v[144:147]
	v_mfma_f32_16x16x32_bf16 v[144:147], v[178:181], v[84:87], v[80:83]
	v_mfma_f32_16x16x32_bf16 v[80:83], v[72:75], v[182:185], v[132:135]
	v_mfma_f32_16x16x32_bf16 v[132:135], v[76:79], v[186:189], v[80:83]
	v_mfma_f32_16x16x32_bf16 v[80:83], v[170:173], v[182:185], v[128:131]
	v_mfma_f32_16x16x32_bf16 v[128:131], v[178:181], v[186:189], v[80:83]
	v_mfma_f32_16x16x32_bf16 v[80:83], v[72:75], v[194:197], v[116:119]
	v_mfma_f32_16x16x32_bf16 v[116:119], v[76:79], v[198:201], v[80:83]
	v_mfma_f32_16x16x32_bf16 v[80:83], v[170:173], v[194:197], v[112:115]
	v_mfma_f32_16x16x32_bf16 v[112:115], v[178:181], v[198:201], v[80:83]
	v_mfma_f32_16x16x32_bf16 v[80:83], v[72:75], v[202:205], v[100:103]
	v_mfma_f32_16x16x32_bf16 v[100:103], v[76:79], v[212:215], v[80:83]
	v_mfma_f32_16x16x32_bf16 v[80:83], v[170:173], v[202:205], v[96:99]
	v_mfma_f32_16x16x32_bf16 v[148:151], v[76:79], v[84:87], v[148:151]
	v_mfma_f32_16x16x32_bf16 v[96:99], v[178:181], v[212:215], v[80:83]
	s_setprio 0
	s_barrier
	s_add_i32 s12, s20, s9
	v_lshl_add_u64 v[84:85], v[190:191], 0, s[24:25]
	s_mov_b32 m0, s12
	s_nop 0
	ds_read_b128 v[80:83], v177 offset:49152
	ds_read_b128 v[182:185], v177 offset:50176
	ds_read_b128 v[186:189], v177 offset:51200
	ds_read_b128 v[194:197], v177 offset:52224
	ds_read_b128 v[198:201], v177 offset:53248
	ds_read_b128 v[202:205], v177 offset:54272
	ds_read_b128 v[212:215], v177 offset:55296
	ds_read_b128 v[242:245], v177 offset:56320
	global_load_lds_dwordx4 v[84:85], off
	v_lshl_add_u64 v[84:85], v[206:207], 0, s[24:25]
	s_add_i32 m0, s12, 0x2000
	s_add_i32 s12, s36, s9
	global_load_lds_dwordx4 v[84:85], off
	v_lshl_add_u64 v[84:85], v[208:209], 0, s[24:25]
	s_mov_b32 m0, s12
	s_nop 0
	global_load_lds_dwordx4 v[84:85], off
	v_lshl_add_u64 v[84:85], v[232:233], 0, s[24:25]
	s_add_i32 m0, s12, 0x2000
	s_nop 0
	global_load_lds_dwordx4 v[84:85], off
	v_lshl_add_u64 v[84:85], v[246:247], 0, s[24:25]
	s_mov_b32 m0, s76
	s_nop 0
	global_load_lds_dwordx4 v[84:85], off
	v_lshl_add_u64 v[84:85], v[248:249], 0, s[24:25]
	s_mov_b32 m0, s77
	s_nop 0
	global_load_lds_dwordx4 v[84:85], off
	s_waitcnt vmcnt(8)
	s_waitcnt lgkmcnt(0)
	s_barrier
	s_setprio 1
	v_mfma_f32_16x16x32_bf16 v[84:87], v[56:59], v[80:83], v[92:95]
	v_mfma_f32_16x16x32_bf16 v[92:95], v[60:63], v[182:185], v[84:87]
	v_mfma_f32_16x16x32_bf16 v[84:87], v[64:67], v[80:83], v[88:91]
	v_mfma_f32_16x16x32_bf16 v[44:47], v[56:59], v[186:189], v[44:47]
	v_mfma_f32_16x16x32_bf16 v[40:43], v[64:67], v[186:189], v[40:43]
	v_mfma_f32_16x16x32_bf16 v[28:31], v[56:59], v[198:201], v[28:31]
	v_mfma_f32_16x16x32_bf16 v[24:27], v[64:67], v[198:201], v[24:27]
	v_mfma_f32_16x16x32_bf16 v[12:15], v[56:59], v[212:215], v[12:15]
	v_mfma_f32_16x16x32_bf16 v[8:11], v[64:67], v[212:215], v[8:11]
	v_mfma_f32_16x16x32_bf16 v[88:91], v[68:71], v[182:185], v[84:87]
	v_mfma_f32_16x16x32_bf16 v[44:47], v[60:63], v[194:197], v[44:47]
	v_mfma_f32_16x16x32_bf16 v[40:43], v[68:71], v[194:197], v[40:43]
	v_mfma_f32_16x16x32_bf16 v[28:31], v[60:63], v[202:205], v[28:31]
	v_mfma_f32_16x16x32_bf16 v[24:27], v[68:71], v[202:205], v[24:27]
	v_mfma_f32_16x16x32_bf16 v[12:15], v[60:63], v[242:245], v[12:15]
	v_mfma_f32_16x16x32_bf16 v[8:11], v[68:71], v[242:245], v[8:11]
	v_mfma_f32_16x16x32_bf16 v[48:51], v[72:75], v[80:83], v[48:51]
	v_mfma_f32_16x16x32_bf16 v[84:87], v[76:79], v[182:185], v[48:51]
	v_mfma_f32_16x16x32_bf16 v[48:51], v[170:173], v[80:83], v[52:55]
	v_mfma_f32_16x16x32_bf16 v[36:39], v[72:75], v[186:189], v[36:39]
	v_mfma_f32_16x16x32_bf16 v[32:35], v[170:173], v[186:189], v[32:35]
	v_mfma_f32_16x16x32_bf16 v[20:23], v[72:75], v[198:201], v[20:23]
	v_mfma_f32_16x16x32_bf16 v[16:19], v[170:173], v[198:201], v[16:19]
	v_mfma_f32_16x16x32_bf16 v[4:7], v[72:75], v[212:215], v[4:7]
	v_mfma_f32_16x16x32_bf16 v[0:3], v[170:173], v[212:215], v[0:3]
	v_mfma_f32_16x16x32_bf16 v[80:83], v[178:181], v[182:185], v[48:51]
	v_mfma_f32_16x16x32_bf16 v[36:39], v[76:79], v[194:197], v[36:39]
	v_mfma_f32_16x16x32_bf16 v[32:35], v[178:181], v[194:197], v[32:35]
	v_mfma_f32_16x16x32_bf16 v[20:23], v[76:79], v[202:205], v[20:23]
	v_mfma_f32_16x16x32_bf16 v[16:19], v[178:181], v[202:205], v[16:19]
	v_mfma_f32_16x16x32_bf16 v[4:7], v[76:79], v[242:245], v[4:7]
	v_mfma_f32_16x16x32_bf16 v[0:3], v[178:181], v[242:245], v[0:3]
	s_setprio 0
	s_barrier
	s_add_u32 s28, s28, 0x100
	s_addc_u32 s29, s29, 0
	s_add_u32 s18, s18, 0x100
	s_addc_u32 s19, s19, 0
	s_cmp_ge_u32 s21, s11
	s_mov_b32 s20, s21
	s_cbranch_scc0 .LBB0_92

.LBB0_113:
	s_add_i32 s21, s20, 2
	s_add_u32 s12, s28, 0x80
	s_addc_u32 s13, s29, 0
	s_add_i32 s36, 0, 0x10000
	s_cmp_eq_u32 s85, s20
	s_cselect_b32 s59, s5, s13
	s_cselect_b32 s58, s4, s12
	v_add_u32_e32 v142, s36, v145
	s_cselect_b32 s13, s57, s19
	s_cselect_b32 s12, s56, s18
	s_add_i32 s20, 0, 0x14000
	ds_read_b128 v[138:141], v142
	ds_read_b128 v[148:151], v142 offset:1024
	ds_read_b128 v[152:155], v142 offset:2048
	ds_read_b128 v[156:159], v142 offset:3072
	v_add_u32_e32 v142, s20, v145
	ds_read_b128 v[160:163], v142
	ds_read_b128 v[164:167], v142 offset:1024
	ds_read_b128 v[168:171], v142 offset:2048
	ds_read_b128 v[172:175], v142 offset:3072
	v_lshl_add_u64 v[142:143], s[28:29], 0, v[134:135]
	s_add_i32 m0, s77, 0xc000
	ds_read_b128 v[176:179], v147
	ds_read_b128 v[180:183], v147 offset:1024
	ds_read_b128 v[184:187], v147 offset:2048
	ds_read_b128 v[188:191], v147 offset:3072
	ds_read_b128 v[194:197], v147 offset:4096
	ds_read_b128 v[198:201], v147 offset:5120
	ds_read_b128 v[202:205], v147 offset:6144
	ds_read_b128 v[212:215], v147 offset:7168
	global_load_lds_dwordx4 v[142:143], off
	v_lshl_add_u64 v[142:143], s[28:29], 0, v[136:137]
	s_add_i32 m0, s77, 0xe000
	s_nop 0
	global_load_lds_dwordx4 v[142:143], off
	s_waitcnt vmcnt(8)
	s_waitcnt lgkmcnt(0)
	s_barrier
	s_setprio 1
	v_mfma_f32_16x16x32_bf16 v[124:127], v[138:141], v[176:179], v[124:127]
	v_mfma_f32_16x16x32_bf16 v[120:123], v[152:155], v[176:179], v[120:123]
	v_mfma_f32_16x16x32_bf16 v[108:111], v[138:141], v[184:187], v[108:111]
	v_mfma_f32_16x16x32_bf16 v[104:107], v[152:155], v[184:187], v[104:107]
	v_mfma_f32_16x16x32_bf16 v[92:95], v[138:141], v[194:197], v[92:95]
	v_mfma_f32_16x16x32_bf16 v[88:91], v[152:155], v[194:197], v[88:91]
	v_mfma_f32_16x16x32_bf16 v[76:79], v[138:141], v[202:205], v[76:79]
	v_mfma_f32_16x16x32_bf16 v[72:75], v[152:155], v[202:205], v[72:75]
	v_mfma_f32_16x16x32_bf16 v[124:127], v[148:151], v[180:183], v[124:127]
	v_mfma_f32_16x16x32_bf16 v[120:123], v[156:159], v[180:183], v[120:123]
	v_mfma_f32_16x16x32_bf16 v[108:111], v[148:151], v[188:191], v[108:111]
	v_mfma_f32_16x16x32_bf16 v[104:107], v[156:159], v[188:191], v[104:107]
	v_mfma_f32_16x16x32_bf16 v[92:95], v[148:151], v[198:201], v[92:95]
	v_mfma_f32_16x16x32_bf16 v[88:91], v[156:159], v[198:201], v[88:91]
	v_mfma_f32_16x16x32_bf16 v[76:79], v[148:151], v[212:215], v[76:79]
	v_mfma_f32_16x16x32_bf16 v[72:75], v[156:159], v[212:215], v[72:75]
	v_mfma_f32_16x16x32_bf16 v[116:119], v[160:163], v[176:179], v[116:119]
	v_mfma_f32_16x16x32_bf16 v[112:115], v[168:171], v[176:179], v[112:115]
	v_mfma_f32_16x16x32_bf16 v[100:103], v[160:163], v[184:187], v[100:103]
	v_mfma_f32_16x16x32_bf16 v[96:99], v[168:171], v[184:187], v[96:99]
	v_mfma_f32_16x16x32_bf16 v[84:87], v[160:163], v[194:197], v[84:87]
	v_mfma_f32_16x16x32_bf16 v[80:83], v[168:171], v[194:197], v[80:83]
	v_mfma_f32_16x16x32_bf16 v[68:71], v[160:163], v[202:205], v[68:71]
	v_mfma_f32_16x16x32_bf16 v[64:67], v[168:171], v[202:205], v[64:67]
	v_mfma_f32_16x16x32_bf16 v[116:119], v[164:167], v[180:183], v[116:119]
	v_mfma_f32_16x16x32_bf16 v[112:115], v[172:175], v[180:183], v[112:115]
	v_mfma_f32_16x16x32_bf16 v[100:103], v[164:167], v[188:191], v[100:103]
	v_mfma_f32_16x16x32_bf16 v[96:99], v[172:175], v[188:191], v[96:99]
	v_mfma_f32_16x16x32_bf16 v[84:87], v[164:167], v[198:201], v[84:87]
	v_mfma_f32_16x16x32_bf16 v[80:83], v[172:175], v[198:201], v[80:83]
	v_mfma_f32_16x16x32_bf16 v[68:71], v[164:167], v[212:215], v[68:71]
	v_mfma_f32_16x16x32_bf16 v[64:67], v[172:175], v[212:215], v[64:67]
	s_setprio 0
	s_barrier
	s_add_i32 s36, s36, s71
	v_lshl_add_u64 v[142:143], s[12:13], 0, v[192:193]
	s_mov_b32 m0, s36
	ds_read_b128 v[176:179], v147 offset:16384
	ds_read_b128 v[180:183], v147 offset:17408
	ds_read_b128 v[184:187], v147 offset:18432
	ds_read_b128 v[188:191], v147 offset:19456
	ds_read_b128 v[194:197], v147 offset:20480
	ds_read_b128 v[198:201], v147 offset:21504
	ds_read_b128 v[202:205], v147 offset:22528
	ds_read_b128 v[212:215], v147 offset:23552
	global_load_lds_dwordx4 v[142:143], off
	s_add_i32 m0, s36, 0x2000
	v_lshl_add_u64 v[206:207], s[12:13], 0, v[128:129]
	s_add_u32 s12, s12, s9
	s_addc_u32 s13, s13, 0
	s_add_i32 s20, s20, s71
	global_load_lds_dwordx4 v[206:207], off
	v_lshl_add_u64 v[208:209], s[12:13], 0, v[192:193]
	s_mov_b32 m0, s20
	v_lshl_add_u64 v[232:233], s[12:13], 0, v[128:129]
	global_load_lds_dwordx4 v[208:209], off
	s_add_i32 m0, s20, 0x2000
	v_lshl_add_u64 v[242:243], s[58:59], 0, v[132:133]
	global_load_lds_dwordx4 v[232:233], off
	s_mov_b32 m0, s77
	v_lshl_add_u64 v[244:245], s[58:59], 0, v[130:131]
	global_load_lds_dwordx4 v[242:243], off
	s_mov_b32 m0, s78
	s_nop 0
	global_load_lds_dwordx4 v[244:245], off
	s_waitcnt vmcnt(8)
	s_waitcnt lgkmcnt(0)
	s_barrier
	s_setprio 1
	v_mfma_f32_16x16x32_bf16 v[60:63], v[138:141], v[176:179], v[60:63]
	v_mfma_f32_16x16x32_bf16 v[56:59], v[152:155], v[176:179], v[56:59]
	v_mfma_f32_16x16x32_bf16 v[44:47], v[138:141], v[184:187], v[44:47]
	v_mfma_f32_16x16x32_bf16 v[40:43], v[152:155], v[184:187], v[40:43]
	v_mfma_f32_16x16x32_bf16 v[28:31], v[138:141], v[194:197], v[28:31]
	v_mfma_f32_16x16x32_bf16 v[24:27], v[152:155], v[194:197], v[24:27]
	v_mfma_f32_16x16x32_bf16 v[12:15], v[138:141], v[202:205], v[12:15]
	v_mfma_f32_16x16x32_bf16 v[8:11], v[152:155], v[202:205], v[8:11]
	v_mfma_f32_16x16x32_bf16 v[60:63], v[148:151], v[180:183], v[60:63]
	v_mfma_f32_16x16x32_bf16 v[56:59], v[156:159], v[180:183], v[56:59]
	v_mfma_f32_16x16x32_bf16 v[44:47], v[148:151], v[188:191], v[44:47]
	v_mfma_f32_16x16x32_bf16 v[40:43], v[156:159], v[188:191], v[40:43]
	v_mfma_f32_16x16x32_bf16 v[28:31], v[148:151], v[198:201], v[28:31]
	v_mfma_f32_16x16x32_bf16 v[24:27], v[156:159], v[198:201], v[24:27]
	v_mfma_f32_16x16x32_bf16 v[12:15], v[148:151], v[212:215], v[12:15]
	v_mfma_f32_16x16x32_bf16 v[8:11], v[156:159], v[212:215], v[8:11]
	v_mfma_f32_16x16x32_bf16 v[52:55], v[160:163], v[176:179], v[52:55]
	v_mfma_f32_16x16x32_bf16 v[48:51], v[168:171], v[176:179], v[48:51]
	v_mfma_f32_16x16x32_bf16 v[36:39], v[160:163], v[184:187], v[36:39]
	v_mfma_f32_16x16x32_bf16 v[32:35], v[168:171], v[184:187], v[32:35]
	v_mfma_f32_16x16x32_bf16 v[20:23], v[160:163], v[194:197], v[20:23]
	v_mfma_f32_16x16x32_bf16 v[16:19], v[168:171], v[194:197], v[16:19]
	v_mfma_f32_16x16x32_bf16 v[4:7], v[160:163], v[202:205], v[4:7]
	v_mfma_f32_16x16x32_bf16 v[0:3], v[168:171], v[202:205], v[0:3]
	v_mfma_f32_16x16x32_bf16 v[52:55], v[164:167], v[180:183], v[52:55]
	v_mfma_f32_16x16x32_bf16 v[48:51], v[172:175], v[180:183], v[48:51]
	v_mfma_f32_16x16x32_bf16 v[36:39], v[164:167], v[188:191], v[36:39]
	v_mfma_f32_16x16x32_bf16 v[32:35], v[172:175], v[188:191], v[32:35]
	v_mfma_f32_16x16x32_bf16 v[20:23], v[164:167], v[198:201], v[20:23]
	v_mfma_f32_16x16x32_bf16 v[16:19], v[172:175], v[198:201], v[16:19]
	v_mfma_f32_16x16x32_bf16 v[4:7], v[164:167], v[212:215], v[4:7]
	v_mfma_f32_16x16x32_bf16 v[0:3], v[172:175], v[212:215], v[0:3]
	s_setprio 0
	s_barrier
	s_add_i32 s20, 0, 0x18000
	s_add_i32 s36, 0, 0x1c000
	v_add_u32_e32 v156, s20, v145
	v_add_u32_e32 v172, s36, v145
	ds_read_b128 v[138:141], v156
	ds_read_b128 v[148:151], v156 offset:1024
	ds_read_b128 v[152:155], v156 offset:2048
	ds_read_b128 v[156:159], v156 offset:3072
	ds_read_b128 v[160:163], v172
	ds_read_b128 v[164:167], v172 offset:1024
	ds_read_b128 v[168:171], v172 offset:2048
	ds_read_b128 v[172:175], v172 offset:3072
	s_add_u32 s12, s58, s34
	s_addc_u32 s13, s59, 0
	s_mov_b32 m0, s79
	v_lshl_add_u64 v[246:247], s[12:13], 0, v[132:133]
	ds_read_b128 v[176:179], v147 offset:32768
	ds_read_b128 v[180:183], v147 offset:33792
	ds_read_b128 v[184:187], v147 offset:34816
	ds_read_b128 v[188:191], v147 offset:35840
	ds_read_b128 v[194:197], v147 offset:36864
	ds_read_b128 v[198:201], v147 offset:37888
	ds_read_b128 v[202:205], v147 offset:38912
	ds_read_b128 v[212:215], v147 offset:39936
	global_load_lds_dwordx4 v[246:247], off
	v_lshl_add_u64 v[246:247], s[12:13], 0, v[130:131]
	s_mov_b32 m0, s80
	s_nop 0
	global_load_lds_dwordx4 v[246:247], off
	s_waitcnt vmcnt(8)
	s_waitcnt lgkmcnt(0)
	s_barrier
	s_setprio 1
	v_mfma_f32_16x16x32_bf16 v[124:127], v[138:141], v[176:179], v[124:127]
	v_mfma_f32_16x16x32_bf16 v[120:123], v[152:155], v[176:179], v[120:123]
	v_mfma_f32_16x16x32_bf16 v[108:111], v[138:141], v[184:187], v[108:111]
	v_mfma_f32_16x16x32_bf16 v[104:107], v[152:155], v[184:187], v[104:107]
	v_mfma_f32_16x16x32_bf16 v[92:95], v[138:141], v[194:197], v[92:95]
	v_mfma_f32_16x16x32_bf16 v[88:91], v[152:155], v[194:197], v[88:91]
	v_mfma_f32_16x16x32_bf16 v[76:79], v[138:141], v[202:205], v[76:79]
	v_mfma_f32_16x16x32_bf16 v[72:75], v[152:155], v[202:205], v[72:75]
	v_mfma_f32_16x16x32_bf16 v[124:127], v[148:151], v[180:183], v[124:127]
	v_mfma_f32_16x16x32_bf16 v[120:123], v[156:159], v[180:183], v[120:123]
	v_mfma_f32_16x16x32_bf16 v[108:111], v[148:151], v[188:191], v[108:111]
	v_mfma_f32_16x16x32_bf16 v[104:107], v[156:159], v[188:191], v[104:107]
	v_mfma_f32_16x16x32_bf16 v[92:95], v[148:151], v[198:201], v[92:95]
	v_mfma_f32_16x16x32_bf16 v[88:91], v[156:159], v[198:201], v[88:91]
	v_mfma_f32_16x16x32_bf16 v[76:79], v[148:151], v[212:215], v[76:79]
	v_mfma_f32_16x16x32_bf16 v[72:75], v[156:159], v[212:215], v[72:75]
	v_mfma_f32_16x16x32_bf16 v[116:119], v[160:163], v[176:179], v[116:119]
	v_mfma_f32_16x16x32_bf16 v[112:115], v[168:171], v[176:179], v[112:115]
	v_mfma_f32_16x16x32_bf16 v[100:103], v[160:163], v[184:187], v[100:103]
	v_mfma_f32_16x16x32_bf16 v[96:99], v[168:171], v[184:187], v[96:99]
	v_mfma_f32_16x16x32_bf16 v[84:87], v[160:163], v[194:197], v[84:87]
	v_mfma_f32_16x16x32_bf16 v[80:83], v[168:171], v[194:197], v[80:83]
	v_mfma_f32_16x16x32_bf16 v[68:71], v[160:163], v[202:205], v[68:71]
	v_mfma_f32_16x16x32_bf16 v[64:67], v[168:171], v[202:205], v[64:67]
	v_mfma_f32_16x16x32_bf16 v[116:119], v[164:167], v[180:183], v[116:119]
	v_mfma_f32_16x16x32_bf16 v[112:115], v[172:175], v[180:183], v[112:115]
	v_mfma_f32_16x16x32_bf16 v[100:103], v[164:167], v[188:191], v[100:103]
	v_mfma_f32_16x16x32_bf16 v[96:99], v[172:175], v[188:191], v[96:99]
	v_mfma_f32_16x16x32_bf16 v[84:87], v[164:167], v[198:201], v[84:87]
	v_mfma_f32_16x16x32_bf16 v[80:83], v[172:175], v[198:201], v[80:83]
	v_mfma_f32_16x16x32_bf16 v[68:71], v[164:167], v[212:215], v[68:71]
	v_mfma_f32_16x16x32_bf16 v[64:67], v[172:175], v[212:215], v[64:67]
	s_setprio 0
	s_barrier
	s_add_i32 s12, s20, s71
	v_lshl_add_u64 v[142:143], v[142:143], 0, s[24:25]
	s_mov_b32 m0, s12
	ds_read_b128 v[176:179], v147 offset:49152
	ds_read_b128 v[180:183], v147 offset:50176
	ds_read_b128 v[184:187], v147 offset:51200
	ds_read_b128 v[188:191], v147 offset:52224
	ds_read_b128 v[194:197], v147 offset:53248
	ds_read_b128 v[198:201], v147 offset:54272
	ds_read_b128 v[202:205], v147 offset:55296
	ds_read_b128 v[212:215], v147 offset:56320
	global_load_lds_dwordx4 v[142:143], off
	v_lshl_add_u64 v[142:143], v[206:207], 0, s[24:25]
	s_add_i32 m0, s12, 0x2000
	s_add_i32 s12, s36, s71
	global_load_lds_dwordx4 v[142:143], off
	v_lshl_add_u64 v[142:143], v[208:209], 0, s[24:25]
	s_mov_b32 m0, s12
	s_nop 0
	global_load_lds_dwordx4 v[142:143], off
	v_lshl_add_u64 v[142:143], v[232:233], 0, s[24:25]
	s_add_i32 m0, s12, 0x2000
	s_nop 0
	global_load_lds_dwordx4 v[142:143], off
	v_lshl_add_u64 v[142:143], v[242:243], 0, s[24:25]
	s_mov_b32 m0, s81
	s_nop 0
	global_load_lds_dwordx4 v[142:143], off
	v_lshl_add_u64 v[142:143], v[244:245], 0, s[24:25]
	s_mov_b32 m0, s82
	s_nop 0
	global_load_lds_dwordx4 v[142:143], off
	s_waitcnt vmcnt(8)
	s_waitcnt lgkmcnt(0)
	s_barrier
	s_setprio 1
	v_mfma_f32_16x16x32_bf16 v[60:63], v[138:141], v[176:179], v[60:63]
	v_mfma_f32_16x16x32_bf16 v[56:59], v[152:155], v[176:179], v[56:59]
	v_mfma_f32_16x16x32_bf16 v[44:47], v[138:141], v[184:187], v[44:47]
	v_mfma_f32_16x16x32_bf16 v[40:43], v[152:155], v[184:187], v[40:43]
	v_mfma_f32_16x16x32_bf16 v[28:31], v[138:141], v[194:197], v[28:31]
	v_mfma_f32_16x16x32_bf16 v[24:27], v[152:155], v[194:197], v[24:27]
	v_mfma_f32_16x16x32_bf16 v[12:15], v[138:141], v[202:205], v[12:15]
	v_mfma_f32_16x16x32_bf16 v[8:11], v[152:155], v[202:205], v[8:11]
	v_mfma_f32_16x16x32_bf16 v[60:63], v[148:151], v[180:183], v[60:63]
	v_mfma_f32_16x16x32_bf16 v[56:59], v[156:159], v[180:183], v[56:59]
	v_mfma_f32_16x16x32_bf16 v[44:47], v[148:151], v[188:191], v[44:47]
	v_mfma_f32_16x16x32_bf16 v[40:43], v[156:159], v[188:191], v[40:43]
	v_mfma_f32_16x16x32_bf16 v[28:31], v[148:151], v[198:201], v[28:31]
	v_mfma_f32_16x16x32_bf16 v[24:27], v[156:159], v[198:201], v[24:27]
	v_mfma_f32_16x16x32_bf16 v[12:15], v[148:151], v[212:215], v[12:15]
	v_mfma_f32_16x16x32_bf16 v[8:11], v[156:159], v[212:215], v[8:11]
	v_mfma_f32_16x16x32_bf16 v[52:55], v[160:163], v[176:179], v[52:55]
	v_mfma_f32_16x16x32_bf16 v[48:51], v[168:171], v[176:179], v[48:51]
	v_mfma_f32_16x16x32_bf16 v[36:39], v[160:163], v[184:187], v[36:39]
	v_mfma_f32_16x16x32_bf16 v[32:35], v[168:171], v[184:187], v[32:35]
	v_mfma_f32_16x16x32_bf16 v[20:23], v[160:163], v[194:197], v[20:23]
	v_mfma_f32_16x16x32_bf16 v[16:19], v[168:171], v[194:197], v[16:19]
	v_mfma_f32_16x16x32_bf16 v[4:7], v[160:163], v[202:205], v[4:7]
	v_mfma_f32_16x16x32_bf16 v[0:3], v[168:171], v[202:205], v[0:3]
	v_mfma_f32_16x16x32_bf16 v[52:55], v[164:167], v[180:183], v[52:55]
	v_mfma_f32_16x16x32_bf16 v[48:51], v[172:175], v[180:183], v[48:51]
	v_mfma_f32_16x16x32_bf16 v[36:39], v[164:167], v[188:191], v[36:39]
	v_mfma_f32_16x16x32_bf16 v[32:35], v[172:175], v[188:191], v[32:35]
	v_mfma_f32_16x16x32_bf16 v[20:23], v[164:167], v[198:201], v[20:23]
	v_mfma_f32_16x16x32_bf16 v[16:19], v[172:175], v[198:201], v[16:19]
	v_mfma_f32_16x16x32_bf16 v[4:7], v[164:167], v[212:215], v[4:7]
	v_mfma_f32_16x16x32_bf16 v[0:3], v[172:175], v[212:215], v[0:3]
	s_setprio 0
	s_barrier
	s_add_u32 s28, s28, 0x100
	s_addc_u32 s29, s29, 0
	s_add_u32 s18, s18, 0x100
	s_addc_u32 s19, s19, 0
	s_cmp_ge_u32 s21, s83
	s_mov_b32 s20, s21
	s_cbranch_scc0 .LBB0_113
	s_and_b64 vcc, exec, s[54:55]
	s_cbranch_vccz .LBB0_116

.LBB0_137:
	s_add_i32 s21, s20, 2
	s_add_u32 s12, s28, 0x80
	s_addc_u32 s13, s29, 0
	s_add_i32 s36, 0, 0x10000
	s_cmp_eq_u32 s81, s20
	s_cselect_b32 s55, s5, s13
	s_cselect_b32 s54, s4, s12
	s_cselect_b32 s13, s53, s19
	s_cselect_b32 s12, s52, s18
	s_add_i32 s20, 0, 0x14000
	v_add_u32_e32 v154, s36, v139
	v_add_u32_e32 v170, s20, v139
	ds_read_b128 v[142:145], v154
	ds_read_b128 v[146:149], v154 offset:1024
	ds_read_b128 v[150:153], v154 offset:2048
	ds_read_b128 v[154:157], v154 offset:3072
	ds_read_b128 v[158:161], v170
	ds_read_b128 v[162:165], v170 offset:1024
	ds_read_b128 v[166:169], v170 offset:2048
	ds_read_b128 v[170:173], v170 offset:3072
	v_lshl_add_u64 v[190:191], s[28:29], 0, v[134:135]
	s_add_i32 m0, s73, 0xc000
	ds_read_b128 v[174:177], v141
	ds_read_b128 v[178:181], v141 offset:1024
	ds_read_b128 v[182:185], v141 offset:2048
	ds_read_b128 v[186:189], v141 offset:3072
	ds_read_b128 v[194:197], v141 offset:4096
	ds_read_b128 v[198:201], v141 offset:5120
	ds_read_b128 v[202:205], v141 offset:6144
	ds_read_b128 v[212:215], v141 offset:7168
	global_load_lds_dwordx4 v[190:191], off
	v_lshl_add_u64 v[190:191], s[28:29], 0, v[136:137]
	s_add_i32 m0, s73, 0xe000
	s_nop 0
	global_load_lds_dwordx4 v[190:191], off
	s_waitcnt vmcnt(8)
	s_waitcnt lgkmcnt(0)
	s_barrier
	s_setprio 1
	v_mfma_f32_16x16x32_bf16 v[124:127], v[142:145], v[174:177], v[124:127]
	v_mfma_f32_16x16x32_bf16 v[116:119], v[150:153], v[174:177], v[116:119]
	v_mfma_f32_16x16x32_bf16 v[108:111], v[142:145], v[182:185], v[108:111]
	v_mfma_f32_16x16x32_bf16 v[100:103], v[150:153], v[182:185], v[100:103]
	v_mfma_f32_16x16x32_bf16 v[92:95], v[142:145], v[194:197], v[92:95]
	v_mfma_f32_16x16x32_bf16 v[84:87], v[150:153], v[194:197], v[84:87]
	v_mfma_f32_16x16x32_bf16 v[76:79], v[142:145], v[202:205], v[76:79]
	v_mfma_f32_16x16x32_bf16 v[68:71], v[150:153], v[202:205], v[68:71]
	v_mfma_f32_16x16x32_bf16 v[124:127], v[146:149], v[178:181], v[124:127]
	v_mfma_f32_16x16x32_bf16 v[116:119], v[154:157], v[178:181], v[116:119]
	v_mfma_f32_16x16x32_bf16 v[108:111], v[146:149], v[186:189], v[108:111]
	v_mfma_f32_16x16x32_bf16 v[100:103], v[154:157], v[186:189], v[100:103]
	v_mfma_f32_16x16x32_bf16 v[92:95], v[146:149], v[198:201], v[92:95]
	v_mfma_f32_16x16x32_bf16 v[84:87], v[154:157], v[198:201], v[84:87]
	v_mfma_f32_16x16x32_bf16 v[76:79], v[146:149], v[212:215], v[76:79]
	v_mfma_f32_16x16x32_bf16 v[68:71], v[154:157], v[212:215], v[68:71]
	v_mfma_f32_16x16x32_bf16 v[120:123], v[158:161], v[174:177], v[120:123]
	v_mfma_f32_16x16x32_bf16 v[112:115], v[166:169], v[174:177], v[112:115]
	v_mfma_f32_16x16x32_bf16 v[104:107], v[158:161], v[182:185], v[104:107]
	v_mfma_f32_16x16x32_bf16 v[96:99], v[166:169], v[182:185], v[96:99]
	v_mfma_f32_16x16x32_bf16 v[88:91], v[158:161], v[194:197], v[88:91]
	v_mfma_f32_16x16x32_bf16 v[80:83], v[166:169], v[194:197], v[80:83]
	v_mfma_f32_16x16x32_bf16 v[72:75], v[158:161], v[202:205], v[72:75]
	v_mfma_f32_16x16x32_bf16 v[64:67], v[166:169], v[202:205], v[64:67]
	v_mfma_f32_16x16x32_bf16 v[120:123], v[162:165], v[178:181], v[120:123]
	v_mfma_f32_16x16x32_bf16 v[112:115], v[170:173], v[178:181], v[112:115]
	v_mfma_f32_16x16x32_bf16 v[104:107], v[162:165], v[186:189], v[104:107]
	v_mfma_f32_16x16x32_bf16 v[96:99], v[170:173], v[186:189], v[96:99]
	v_mfma_f32_16x16x32_bf16 v[88:91], v[162:165], v[198:201], v[88:91]
	v_mfma_f32_16x16x32_bf16 v[80:83], v[170:173], v[198:201], v[80:83]
	v_mfma_f32_16x16x32_bf16 v[72:75], v[162:165], v[212:215], v[72:75]
	v_mfma_f32_16x16x32_bf16 v[64:67], v[170:173], v[212:215], v[64:67]
	s_setprio 0
	s_barrier
	s_add_i32 s36, s36, s57
	v_lshl_add_u64 v[190:191], s[12:13], 0, v[192:193]
	s_mov_b32 m0, s36
	ds_read_b128 v[174:177], v141 offset:16384
	ds_read_b128 v[178:181], v141 offset:17408
	ds_read_b128 v[182:185], v141 offset:18432
	ds_read_b128 v[186:189], v141 offset:19456
	ds_read_b128 v[194:197], v141 offset:20480
	ds_read_b128 v[198:201], v141 offset:21504
	ds_read_b128 v[202:205], v141 offset:22528
	ds_read_b128 v[212:215], v141 offset:23552
	global_load_lds_dwordx4 v[190:191], off
	s_add_i32 m0, s36, 0x2000
	v_lshl_add_u64 v[206:207], s[12:13], 0, v[128:129]
	s_add_u32 s12, s12, s9
	s_addc_u32 s13, s13, 0
	s_add_i32 s20, s20, s57
	global_load_lds_dwordx4 v[206:207], off
	v_lshl_add_u64 v[208:209], s[12:13], 0, v[192:193]
	s_mov_b32 m0, s20
	v_lshl_add_u64 v[232:233], s[12:13], 0, v[128:129]
	global_load_lds_dwordx4 v[208:209], off
	s_add_i32 m0, s20, 0x2000
	v_lshl_add_u64 v[242:243], s[54:55], 0, v[132:133]
	global_load_lds_dwordx4 v[232:233], off
	s_mov_b32 m0, s73
	v_lshl_add_u64 v[244:245], s[54:55], 0, v[130:131]
	global_load_lds_dwordx4 v[242:243], off
	s_mov_b32 m0, s74
	s_nop 0
	global_load_lds_dwordx4 v[244:245], off
	s_waitcnt vmcnt(8)
	s_waitcnt lgkmcnt(0)
	s_barrier
	s_setprio 1
	v_mfma_f32_16x16x32_bf16 v[60:63], v[142:145], v[174:177], v[60:63]
	v_mfma_f32_16x16x32_bf16 v[52:55], v[150:153], v[174:177], v[52:55]
	v_mfma_f32_16x16x32_bf16 v[44:47], v[142:145], v[182:185], v[44:47]
	v_mfma_f32_16x16x32_bf16 v[36:39], v[150:153], v[182:185], v[36:39]
	v_mfma_f32_16x16x32_bf16 v[28:31], v[142:145], v[194:197], v[28:31]
	v_mfma_f32_16x16x32_bf16 v[20:23], v[150:153], v[194:197], v[20:23]
	v_mfma_f32_16x16x32_bf16 v[12:15], v[142:145], v[202:205], v[12:15]
	v_mfma_f32_16x16x32_bf16 v[4:7], v[150:153], v[202:205], v[4:7]
	v_mfma_f32_16x16x32_bf16 v[60:63], v[146:149], v[178:181], v[60:63]
	v_mfma_f32_16x16x32_bf16 v[52:55], v[154:157], v[178:181], v[52:55]
	v_mfma_f32_16x16x32_bf16 v[44:47], v[146:149], v[186:189], v[44:47]
	v_mfma_f32_16x16x32_bf16 v[36:39], v[154:157], v[186:189], v[36:39]
	v_mfma_f32_16x16x32_bf16 v[28:31], v[146:149], v[198:201], v[28:31]
	v_mfma_f32_16x16x32_bf16 v[20:23], v[154:157], v[198:201], v[20:23]
	v_mfma_f32_16x16x32_bf16 v[12:15], v[146:149], v[212:215], v[12:15]
	v_mfma_f32_16x16x32_bf16 v[4:7], v[154:157], v[212:215], v[4:7]
	v_mfma_f32_16x16x32_bf16 v[56:59], v[158:161], v[174:177], v[56:59]
	v_mfma_f32_16x16x32_bf16 v[48:51], v[166:169], v[174:177], v[48:51]
	v_mfma_f32_16x16x32_bf16 v[40:43], v[158:161], v[182:185], v[40:43]
	v_mfma_f32_16x16x32_bf16 v[32:35], v[166:169], v[182:185], v[32:35]
	v_mfma_f32_16x16x32_bf16 v[24:27], v[158:161], v[194:197], v[24:27]
	v_mfma_f32_16x16x32_bf16 v[16:19], v[166:169], v[194:197], v[16:19]
	v_mfma_f32_16x16x32_bf16 v[8:11], v[158:161], v[202:205], v[8:11]
	v_mfma_f32_16x16x32_bf16 v[0:3], v[166:169], v[202:205], v[0:3]
	v_mfma_f32_16x16x32_bf16 v[56:59], v[162:165], v[178:181], v[56:59]
	v_mfma_f32_16x16x32_bf16 v[48:51], v[170:173], v[178:181], v[48:51]
	v_mfma_f32_16x16x32_bf16 v[40:43], v[162:165], v[186:189], v[40:43]
	v_mfma_f32_16x16x32_bf16 v[32:35], v[170:173], v[186:189], v[32:35]
	v_mfma_f32_16x16x32_bf16 v[24:27], v[162:165], v[198:201], v[24:27]
	v_mfma_f32_16x16x32_bf16 v[16:19], v[170:173], v[198:201], v[16:19]
	v_mfma_f32_16x16x32_bf16 v[8:11], v[162:165], v[212:215], v[8:11]
	v_mfma_f32_16x16x32_bf16 v[0:3], v[170:173], v[212:215], v[0:3]
	s_setprio 0
	s_barrier
	s_add_i32 s20, 0, 0x18000
	s_add_i32 s36, 0, 0x1c000
	v_add_u32_e32 v154, s20, v139
	v_add_u32_e32 v170, s36, v139
	ds_read_b128 v[142:145], v154
	ds_read_b128 v[146:149], v154 offset:1024
	ds_read_b128 v[150:153], v154 offset:2048
	ds_read_b128 v[154:157], v154 offset:3072
	ds_read_b128 v[158:161], v170
	ds_read_b128 v[162:165], v170 offset:1024
	ds_read_b128 v[166:169], v170 offset:2048
	ds_read_b128 v[170:173], v170 offset:3072
	s_add_u32 s12, s54, s34
	s_addc_u32 s13, s55, 0
	s_mov_b32 m0, s75
	v_lshl_add_u64 v[246:247], s[12:13], 0, v[132:133]
	ds_read_b128 v[174:177], v141 offset:32768
	ds_read_b128 v[178:181], v141 offset:33792
	ds_read_b128 v[182:185], v141 offset:34816
	ds_read_b128 v[186:189], v141 offset:35840
	ds_read_b128 v[194:197], v141 offset:36864
	ds_read_b128 v[198:201], v141 offset:37888
	ds_read_b128 v[202:205], v141 offset:38912
	ds_read_b128 v[212:215], v141 offset:39936
	global_load_lds_dwordx4 v[246:247], off
	v_lshl_add_u64 v[246:247], s[12:13], 0, v[130:131]
	s_mov_b32 m0, s76
	s_nop 0
	global_load_lds_dwordx4 v[246:247], off
	s_waitcnt vmcnt(8)
	s_waitcnt lgkmcnt(0)
	s_barrier
	s_setprio 1
	v_mfma_f32_16x16x32_bf16 v[124:127], v[142:145], v[174:177], v[124:127]
	v_mfma_f32_16x16x32_bf16 v[116:119], v[150:153], v[174:177], v[116:119]
	v_mfma_f32_16x16x32_bf16 v[108:111], v[142:145], v[182:185], v[108:111]
	v_mfma_f32_16x16x32_bf16 v[100:103], v[150:153], v[182:185], v[100:103]
	v_mfma_f32_16x16x32_bf16 v[92:95], v[142:145], v[194:197], v[92:95]
	v_mfma_f32_16x16x32_bf16 v[84:87], v[150:153], v[194:197], v[84:87]
	v_mfma_f32_16x16x32_bf16 v[76:79], v[142:145], v[202:205], v[76:79]
	v_mfma_f32_16x16x32_bf16 v[68:71], v[150:153], v[202:205], v[68:71]
	v_mfma_f32_16x16x32_bf16 v[124:127], v[146:149], v[178:181], v[124:127]
	v_mfma_f32_16x16x32_bf16 v[116:119], v[154:157], v[178:181], v[116:119]
	v_mfma_f32_16x16x32_bf16 v[108:111], v[146:149], v[186:189], v[108:111]
	v_mfma_f32_16x16x32_bf16 v[100:103], v[154:157], v[186:189], v[100:103]
	v_mfma_f32_16x16x32_bf16 v[92:95], v[146:149], v[198:201], v[92:95]
	v_mfma_f32_16x16x32_bf16 v[84:87], v[154:157], v[198:201], v[84:87]
	v_mfma_f32_16x16x32_bf16 v[76:79], v[146:149], v[212:215], v[76:79]
	v_mfma_f32_16x16x32_bf16 v[68:71], v[154:157], v[212:215], v[68:71]
	v_mfma_f32_16x16x32_bf16 v[120:123], v[158:161], v[174:177], v[120:123]
	v_mfma_f32_16x16x32_bf16 v[112:115], v[166:169], v[174:177], v[112:115]
	v_mfma_f32_16x16x32_bf16 v[104:107], v[158:161], v[182:185], v[104:107]
	v_mfma_f32_16x16x32_bf16 v[96:99], v[166:169], v[182:185], v[96:99]
	v_mfma_f32_16x16x32_bf16 v[88:91], v[158:161], v[194:197], v[88:91]
	v_mfma_f32_16x16x32_bf16 v[80:83], v[166:169], v[194:197], v[80:83]
	v_mfma_f32_16x16x32_bf16 v[72:75], v[158:161], v[202:205], v[72:75]
	v_mfma_f32_16x16x32_bf16 v[64:67], v[166:169], v[202:205], v[64:67]
	v_mfma_f32_16x16x32_bf16 v[120:123], v[162:165], v[178:181], v[120:123]
	v_mfma_f32_16x16x32_bf16 v[112:115], v[170:173], v[178:181], v[112:115]
	v_mfma_f32_16x16x32_bf16 v[104:107], v[162:165], v[186:189], v[104:107]
	v_mfma_f32_16x16x32_bf16 v[96:99], v[170:173], v[186:189], v[96:99]
	v_mfma_f32_16x16x32_bf16 v[88:91], v[162:165], v[198:201], v[88:91]
	v_mfma_f32_16x16x32_bf16 v[80:83], v[170:173], v[198:201], v[80:83]
	v_mfma_f32_16x16x32_bf16 v[72:75], v[162:165], v[212:215], v[72:75]
	v_mfma_f32_16x16x32_bf16 v[64:67], v[170:173], v[212:215], v[64:67]
	s_setprio 0
	s_barrier
	s_add_i32 s12, s20, s57
	v_lshl_add_u64 v[190:191], v[190:191], 0, s[24:25]
	s_mov_b32 m0, s12
	ds_read_b128 v[174:177], v141 offset:49152
	ds_read_b128 v[178:181], v141 offset:50176
	ds_read_b128 v[182:185], v141 offset:51200
	ds_read_b128 v[186:189], v141 offset:52224
	ds_read_b128 v[194:197], v141 offset:53248
	ds_read_b128 v[198:201], v141 offset:54272
	ds_read_b128 v[202:205], v141 offset:55296
	ds_read_b128 v[212:215], v141 offset:56320
	global_load_lds_dwordx4 v[190:191], off
	v_lshl_add_u64 v[190:191], v[206:207], 0, s[24:25]
	s_add_i32 m0, s12, 0x2000
	s_add_i32 s12, s36, s57
	global_load_lds_dwordx4 v[190:191], off
	v_lshl_add_u64 v[190:191], v[208:209], 0, s[24:25]
	s_mov_b32 m0, s12
	s_nop 0
	global_load_lds_dwordx4 v[190:191], off
	v_lshl_add_u64 v[190:191], v[232:233], 0, s[24:25]
	s_add_i32 m0, s12, 0x2000
	s_nop 0
	global_load_lds_dwordx4 v[190:191], off
	v_lshl_add_u64 v[190:191], v[242:243], 0, s[24:25]
	s_mov_b32 m0, s77
	s_nop 0
	global_load_lds_dwordx4 v[190:191], off
	v_lshl_add_u64 v[190:191], v[244:245], 0, s[24:25]
	s_mov_b32 m0, s78
	s_nop 0
	global_load_lds_dwordx4 v[190:191], off
	s_waitcnt vmcnt(8)
	s_waitcnt lgkmcnt(0)
	s_barrier
	s_setprio 1
	v_mfma_f32_16x16x32_bf16 v[60:63], v[142:145], v[174:177], v[60:63]
	v_mfma_f32_16x16x32_bf16 v[52:55], v[150:153], v[174:177], v[52:55]
	v_mfma_f32_16x16x32_bf16 v[44:47], v[142:145], v[182:185], v[44:47]
	v_mfma_f32_16x16x32_bf16 v[36:39], v[150:153], v[182:185], v[36:39]
	v_mfma_f32_16x16x32_bf16 v[28:31], v[142:145], v[194:197], v[28:31]
	v_mfma_f32_16x16x32_bf16 v[20:23], v[150:153], v[194:197], v[20:23]
	v_mfma_f32_16x16x32_bf16 v[12:15], v[142:145], v[202:205], v[12:15]
	v_mfma_f32_16x16x32_bf16 v[4:7], v[150:153], v[202:205], v[4:7]
	v_mfma_f32_16x16x32_bf16 v[60:63], v[146:149], v[178:181], v[60:63]
	v_mfma_f32_16x16x32_bf16 v[52:55], v[154:157], v[178:181], v[52:55]
	v_mfma_f32_16x16x32_bf16 v[44:47], v[146:149], v[186:189], v[44:47]
	v_mfma_f32_16x16x32_bf16 v[36:39], v[154:157], v[186:189], v[36:39]
	v_mfma_f32_16x16x32_bf16 v[28:31], v[146:149], v[198:201], v[28:31]
	v_mfma_f32_16x16x32_bf16 v[20:23], v[154:157], v[198:201], v[20:23]
	v_mfma_f32_16x16x32_bf16 v[12:15], v[146:149], v[212:215], v[12:15]
	v_mfma_f32_16x16x32_bf16 v[4:7], v[154:157], v[212:215], v[4:7]
	v_mfma_f32_16x16x32_bf16 v[56:59], v[158:161], v[174:177], v[56:59]
	v_mfma_f32_16x16x32_bf16 v[48:51], v[166:169], v[174:177], v[48:51]
	v_mfma_f32_16x16x32_bf16 v[40:43], v[158:161], v[182:185], v[40:43]
	v_mfma_f32_16x16x32_bf16 v[32:35], v[166:169], v[182:185], v[32:35]
	v_mfma_f32_16x16x32_bf16 v[24:27], v[158:161], v[194:197], v[24:27]
	v_mfma_f32_16x16x32_bf16 v[16:19], v[166:169], v[194:197], v[16:19]
	v_mfma_f32_16x16x32_bf16 v[8:11], v[158:161], v[202:205], v[8:11]
	v_mfma_f32_16x16x32_bf16 v[0:3], v[166:169], v[202:205], v[0:3]
	v_mfma_f32_16x16x32_bf16 v[56:59], v[162:165], v[178:181], v[56:59]
	v_mfma_f32_16x16x32_bf16 v[48:51], v[170:173], v[178:181], v[48:51]
	v_mfma_f32_16x16x32_bf16 v[40:43], v[162:165], v[186:189], v[40:43]
	v_mfma_f32_16x16x32_bf16 v[32:35], v[170:173], v[186:189], v[32:35]
	v_mfma_f32_16x16x32_bf16 v[24:27], v[162:165], v[198:201], v[24:27]
	v_mfma_f32_16x16x32_bf16 v[16:19], v[170:173], v[198:201], v[16:19]
	v_mfma_f32_16x16x32_bf16 v[8:11], v[162:165], v[212:215], v[8:11]
	v_mfma_f32_16x16x32_bf16 v[0:3], v[170:173], v[212:215], v[0:3]
	s_setprio 0
	s_barrier
	s_add_u32 s28, s28, 0x100
	s_addc_u32 s29, s29, 0
	s_add_u32 s18, s18, 0x100
	s_addc_u32 s19, s19, 0
	s_cmp_ge_u32 s21, s79
	s_mov_b32 s20, s21
	s_cbranch_scc0 .LBB0_137
	s_and_b64 vcc, exec, s[50:51]
	s_cbranch_vccz .LBB0_140

.LBB0_161:
	s_add_i32 s21, s20, 2
	s_add_u32 s12, s28, 0x80
	s_addc_u32 s13, s29, 0
	s_add_i32 s36, 0, 0x10000
	s_cmp_eq_u32 s85, s20
	s_cselect_b32 s59, s5, s13
	s_cselect_b32 s58, s4, s12
	v_add_u32_e32 v138, s36, v141
	s_cselect_b32 s13, s57, s19
	s_cselect_b32 s12, s56, s18
	s_add_i32 s20, 0, 0x14000
	ds_read_b128 v[148:151], v138
	ds_read_b128 v[152:155], v138 offset:1024
	ds_read_b128 v[156:159], v138 offset:2048
	ds_read_b128 v[160:163], v138 offset:3072
	v_add_u32_e32 v138, s20, v141
	ds_read_b128 v[164:167], v138
	ds_read_b128 v[168:171], v138 offset:1024
	ds_read_b128 v[172:175], v138 offset:2048
	ds_read_b128 v[176:179], v138 offset:3072
	v_lshl_add_u64 v[144:145], s[28:29], 0, v[134:135]
	s_add_i32 m0, s78, 0xc000
	ds_read_b128 v[180:183], v147
	ds_read_b128 v[184:187], v147 offset:1024
	ds_read_b128 v[188:191], v147 offset:2048
	ds_read_b128 v[194:197], v147 offset:3072
	ds_read_b128 v[198:201], v147 offset:4096
	ds_read_b128 v[202:205], v147 offset:5120
	ds_read_b128 v[212:215], v147 offset:6144
	ds_read_b128 v[242:245], v147 offset:7168
	global_load_lds_dwordx4 v[144:145], off
	v_lshl_add_u64 v[144:145], s[28:29], 0, v[136:137]
	s_add_i32 m0, s78, 0xe000
	s_nop 0
	global_load_lds_dwordx4 v[144:145], off
	s_waitcnt vmcnt(8)
	s_waitcnt lgkmcnt(0)
	s_barrier
	s_setprio 1
	v_mfma_f32_16x16x32_bf16 v[124:127], v[148:151], v[180:183], v[124:127]
	v_mfma_f32_16x16x32_bf16 v[120:123], v[156:159], v[180:183], v[120:123]
	v_mfma_f32_16x16x32_bf16 v[108:111], v[148:151], v[188:191], v[108:111]
	v_mfma_f32_16x16x32_bf16 v[104:107], v[156:159], v[188:191], v[104:107]
	v_mfma_f32_16x16x32_bf16 v[92:95], v[148:151], v[198:201], v[92:95]
	v_mfma_f32_16x16x32_bf16 v[88:91], v[156:159], v[198:201], v[88:91]
	v_mfma_f32_16x16x32_bf16 v[76:79], v[148:151], v[212:215], v[76:79]
	v_mfma_f32_16x16x32_bf16 v[72:75], v[156:159], v[212:215], v[72:75]
	v_mfma_f32_16x16x32_bf16 v[124:127], v[152:155], v[184:187], v[124:127]
	v_mfma_f32_16x16x32_bf16 v[120:123], v[160:163], v[184:187], v[120:123]
	v_mfma_f32_16x16x32_bf16 v[108:111], v[152:155], v[194:197], v[108:111]
	v_mfma_f32_16x16x32_bf16 v[104:107], v[160:163], v[194:197], v[104:107]
	v_mfma_f32_16x16x32_bf16 v[92:95], v[152:155], v[202:205], v[92:95]
	v_mfma_f32_16x16x32_bf16 v[88:91], v[160:163], v[202:205], v[88:91]
	v_mfma_f32_16x16x32_bf16 v[76:79], v[152:155], v[242:245], v[76:79]
	v_mfma_f32_16x16x32_bf16 v[72:75], v[160:163], v[242:245], v[72:75]
	v_mfma_f32_16x16x32_bf16 v[116:119], v[164:167], v[180:183], v[116:119]
	v_mfma_f32_16x16x32_bf16 v[112:115], v[172:175], v[180:183], v[112:115]
	v_mfma_f32_16x16x32_bf16 v[100:103], v[164:167], v[188:191], v[100:103]
	v_mfma_f32_16x16x32_bf16 v[96:99], v[172:175], v[188:191], v[96:99]
	v_mfma_f32_16x16x32_bf16 v[84:87], v[164:167], v[198:201], v[84:87]
	v_mfma_f32_16x16x32_bf16 v[80:83], v[172:175], v[198:201], v[80:83]
	v_mfma_f32_16x16x32_bf16 v[68:71], v[164:167], v[212:215], v[68:71]
	v_mfma_f32_16x16x32_bf16 v[64:67], v[172:175], v[212:215], v[64:67]
	v_mfma_f32_16x16x32_bf16 v[116:119], v[168:171], v[184:187], v[116:119]
	v_mfma_f32_16x16x32_bf16 v[112:115], v[176:179], v[184:187], v[112:115]
	v_mfma_f32_16x16x32_bf16 v[100:103], v[168:171], v[194:197], v[100:103]
	v_mfma_f32_16x16x32_bf16 v[96:99], v[176:179], v[194:197], v[96:99]
	v_mfma_f32_16x16x32_bf16 v[84:87], v[168:171], v[202:205], v[84:87]
	v_mfma_f32_16x16x32_bf16 v[80:83], v[176:179], v[202:205], v[80:83]
	v_mfma_f32_16x16x32_bf16 v[68:71], v[168:171], v[242:245], v[68:71]
	v_mfma_f32_16x16x32_bf16 v[64:67], v[176:179], v[242:245], v[64:67]
	s_setprio 0
	s_barrier
	s_add_i32 s36, s36, s72
	v_lshl_add_u64 v[144:145], s[12:13], 0, v[192:193]
	s_mov_b32 m0, s36
	ds_read_b128 v[180:183], v147 offset:16384
	ds_read_b128 v[184:187], v147 offset:17408
	ds_read_b128 v[188:191], v147 offset:18432
	ds_read_b128 v[194:197], v147 offset:19456
	ds_read_b128 v[198:201], v147 offset:20480
	ds_read_b128 v[202:205], v147 offset:21504
	ds_read_b128 v[212:215], v147 offset:22528
	ds_read_b128 v[242:245], v147 offset:23552
	global_load_lds_dwordx4 v[144:145], off
	s_add_i32 m0, s36, 0x2000
	v_lshl_add_u64 v[206:207], s[12:13], 0, v[128:129]
	s_add_u32 s12, s12, s70
	s_addc_u32 s13, s13, 0
	s_add_i32 s20, s20, s72
	global_load_lds_dwordx4 v[206:207], off
	v_lshl_add_u64 v[246:247], s[12:13], 0, v[192:193]
	s_mov_b32 m0, s20
	v_lshl_add_u64 v[248:249], s[12:13], 0, v[128:129]
	global_load_lds_dwordx4 v[246:247], off
	s_add_i32 m0, s20, 0x2000
	v_lshl_add_u64 v[250:251], s[58:59], 0, v[132:133]
	global_load_lds_dwordx4 v[248:249], off
	s_mov_b32 m0, s78
	v_lshl_add_u64 v[208:209], s[58:59], 0, v[130:131]
	global_load_lds_dwordx4 v[250:251], off
	s_mov_b32 m0, s79
	s_nop 0
	global_load_lds_dwordx4 v[208:209], off
	s_waitcnt vmcnt(8)
	s_waitcnt lgkmcnt(0)
	s_barrier
	s_setprio 1
	v_mfma_f32_16x16x32_bf16 v[60:63], v[148:151], v[180:183], v[60:63]
	v_mfma_f32_16x16x32_bf16 v[56:59], v[156:159], v[180:183], v[56:59]
	v_mfma_f32_16x16x32_bf16 v[44:47], v[148:151], v[188:191], v[44:47]
	v_mfma_f32_16x16x32_bf16 v[40:43], v[156:159], v[188:191], v[40:43]
	v_mfma_f32_16x16x32_bf16 v[28:31], v[148:151], v[198:201], v[28:31]
	v_mfma_f32_16x16x32_bf16 v[24:27], v[156:159], v[198:201], v[24:27]
	v_mfma_f32_16x16x32_bf16 v[12:15], v[148:151], v[212:215], v[12:15]
	v_mfma_f32_16x16x32_bf16 v[8:11], v[156:159], v[212:215], v[8:11]
	v_mfma_f32_16x16x32_bf16 v[60:63], v[152:155], v[184:187], v[60:63]
	v_mfma_f32_16x16x32_bf16 v[56:59], v[160:163], v[184:187], v[56:59]
	v_mfma_f32_16x16x32_bf16 v[44:47], v[152:155], v[194:197], v[44:47]
	v_mfma_f32_16x16x32_bf16 v[40:43], v[160:163], v[194:197], v[40:43]
	v_mfma_f32_16x16x32_bf16 v[28:31], v[152:155], v[202:205], v[28:31]
	v_mfma_f32_16x16x32_bf16 v[24:27], v[160:163], v[202:205], v[24:27]
	v_mfma_f32_16x16x32_bf16 v[12:15], v[152:155], v[242:245], v[12:15]
	v_mfma_f32_16x16x32_bf16 v[8:11], v[160:163], v[242:245], v[8:11]
	v_mfma_f32_16x16x32_bf16 v[52:55], v[164:167], v[180:183], v[52:55]
	v_mfma_f32_16x16x32_bf16 v[48:51], v[172:175], v[180:183], v[48:51]
	v_mfma_f32_16x16x32_bf16 v[36:39], v[164:167], v[188:191], v[36:39]
	v_mfma_f32_16x16x32_bf16 v[32:35], v[172:175], v[188:191], v[32:35]
	v_mfma_f32_16x16x32_bf16 v[20:23], v[164:167], v[198:201], v[20:23]
	v_mfma_f32_16x16x32_bf16 v[16:19], v[172:175], v[198:201], v[16:19]
	v_mfma_f32_16x16x32_bf16 v[4:7], v[164:167], v[212:215], v[4:7]
	v_mfma_f32_16x16x32_bf16 v[0:3], v[172:175], v[212:215], v[0:3]
	v_mfma_f32_16x16x32_bf16 v[52:55], v[168:171], v[184:187], v[52:55]
	v_mfma_f32_16x16x32_bf16 v[48:51], v[176:179], v[184:187], v[48:51]
	v_mfma_f32_16x16x32_bf16 v[36:39], v[168:171], v[194:197], v[36:39]
	v_mfma_f32_16x16x32_bf16 v[32:35], v[176:179], v[194:197], v[32:35]
	v_mfma_f32_16x16x32_bf16 v[20:23], v[168:171], v[202:205], v[20:23]
	v_mfma_f32_16x16x32_bf16 v[16:19], v[176:179], v[202:205], v[16:19]
	v_mfma_f32_16x16x32_bf16 v[4:7], v[168:171], v[242:245], v[4:7]
	v_mfma_f32_16x16x32_bf16 v[0:3], v[176:179], v[242:245], v[0:3]
	s_setprio 0
	s_barrier
	s_add_i32 s20, 0, 0x18000
	v_add_u32_e32 v138, s20, v141
	s_add_i32 s36, 0, 0x1c000
	ds_read_b128 v[148:151], v138
	ds_read_b128 v[152:155], v138 offset:1024
	ds_read_b128 v[156:159], v138 offset:2048
	ds_read_b128 v[160:163], v138 offset:3072
	v_add_u32_e32 v138, s36, v141
	ds_read_b128 v[164:167], v138
	ds_read_b128 v[168:171], v138 offset:1024
	ds_read_b128 v[172:175], v138 offset:2048
	ds_read_b128 v[176:179], v138 offset:3072
	s_add_u32 s12, s58, s34
	s_addc_u32 s13, s59, 0
	s_mov_b32 m0, s80
	v_lshl_add_u64 v[232:233], s[12:13], 0, v[132:133]
	ds_read_b128 v[180:183], v147 offset:32768
	ds_read_b128 v[184:187], v147 offset:33792
	ds_read_b128 v[188:191], v147 offset:34816
	ds_read_b128 v[194:197], v147 offset:35840
	ds_read_b128 v[198:201], v147 offset:36864
	ds_read_b128 v[202:205], v147 offset:37888
	ds_read_b128 v[212:215], v147 offset:38912
	ds_read_b128 v[242:245], v147 offset:39936
	global_load_lds_dwordx4 v[232:233], off
	v_lshl_add_u64 v[232:233], s[12:13], 0, v[130:131]
	s_mov_b32 m0, s81
	s_nop 0
	global_load_lds_dwordx4 v[232:233], off
	s_waitcnt vmcnt(8)
	s_waitcnt lgkmcnt(0)
	s_barrier
	s_setprio 1
	v_mfma_f32_16x16x32_bf16 v[124:127], v[148:151], v[180:183], v[124:127]
	v_mfma_f32_16x16x32_bf16 v[120:123], v[156:159], v[180:183], v[120:123]
	v_mfma_f32_16x16x32_bf16 v[108:111], v[148:151], v[188:191], v[108:111]
	v_mfma_f32_16x16x32_bf16 v[104:107], v[156:159], v[188:191], v[104:107]
	v_mfma_f32_16x16x32_bf16 v[92:95], v[148:151], v[198:201], v[92:95]
	v_mfma_f32_16x16x32_bf16 v[88:91], v[156:159], v[198:201], v[88:91]
	v_mfma_f32_16x16x32_bf16 v[76:79], v[148:151], v[212:215], v[76:79]
	v_mfma_f32_16x16x32_bf16 v[72:75], v[156:159], v[212:215], v[72:75]
	v_mfma_f32_16x16x32_bf16 v[124:127], v[152:155], v[184:187], v[124:127]
	v_mfma_f32_16x16x32_bf16 v[120:123], v[160:163], v[184:187], v[120:123]
	v_mfma_f32_16x16x32_bf16 v[108:111], v[152:155], v[194:197], v[108:111]
	v_mfma_f32_16x16x32_bf16 v[104:107], v[160:163], v[194:197], v[104:107]
	v_mfma_f32_16x16x32_bf16 v[92:95], v[152:155], v[202:205], v[92:95]
	v_mfma_f32_16x16x32_bf16 v[88:91], v[160:163], v[202:205], v[88:91]
	v_mfma_f32_16x16x32_bf16 v[76:79], v[152:155], v[242:245], v[76:79]
	v_mfma_f32_16x16x32_bf16 v[72:75], v[160:163], v[242:245], v[72:75]
	v_mfma_f32_16x16x32_bf16 v[116:119], v[164:167], v[180:183], v[116:119]
	v_mfma_f32_16x16x32_bf16 v[112:115], v[172:175], v[180:183], v[112:115]
	v_mfma_f32_16x16x32_bf16 v[100:103], v[164:167], v[188:191], v[100:103]
	v_mfma_f32_16x16x32_bf16 v[96:99], v[172:175], v[188:191], v[96:99]
	v_mfma_f32_16x16x32_bf16 v[84:87], v[164:167], v[198:201], v[84:87]
	v_mfma_f32_16x16x32_bf16 v[80:83], v[172:175], v[198:201], v[80:83]
	v_mfma_f32_16x16x32_bf16 v[68:71], v[164:167], v[212:215], v[68:71]
	v_mfma_f32_16x16x32_bf16 v[64:67], v[172:175], v[212:215], v[64:67]
	v_mfma_f32_16x16x32_bf16 v[116:119], v[168:171], v[184:187], v[116:119]
	v_mfma_f32_16x16x32_bf16 v[112:115], v[176:179], v[184:187], v[112:115]
	v_mfma_f32_16x16x32_bf16 v[100:103], v[168:171], v[194:197], v[100:103]
	v_mfma_f32_16x16x32_bf16 v[96:99], v[176:179], v[194:197], v[96:99]
	v_mfma_f32_16x16x32_bf16 v[84:87], v[168:171], v[202:205], v[84:87]
	v_mfma_f32_16x16x32_bf16 v[80:83], v[176:179], v[202:205], v[80:83]
	v_mfma_f32_16x16x32_bf16 v[68:71], v[168:171], v[242:245], v[68:71]
	v_mfma_f32_16x16x32_bf16 v[64:67], v[176:179], v[242:245], v[64:67]
	s_setprio 0
	s_barrier
	s_add_i32 s12, s20, s72
	v_lshl_add_u64 v[144:145], v[144:145], 0, s[24:25]
	s_mov_b32 m0, s12
	ds_read_b128 v[180:183], v147 offset:49152
	ds_read_b128 v[184:187], v147 offset:50176
	ds_read_b128 v[188:191], v147 offset:51200
	ds_read_b128 v[194:197], v147 offset:52224
	ds_read_b128 v[198:201], v147 offset:53248
	ds_read_b128 v[202:205], v147 offset:54272
	ds_read_b128 v[212:215], v147 offset:55296
	ds_read_b128 v[242:245], v147 offset:56320
	global_load_lds_dwordx4 v[144:145], off
	v_lshl_add_u64 v[144:145], v[206:207], 0, s[24:25]
	s_add_i32 m0, s12, 0x2000
	s_add_i32 s12, s36, s72
	global_load_lds_dwordx4 v[144:145], off
	v_lshl_add_u64 v[144:145], v[246:247], 0, s[24:25]
	s_mov_b32 m0, s12
	s_nop 0
	global_load_lds_dwordx4 v[144:145], off
	v_lshl_add_u64 v[144:145], v[248:249], 0, s[24:25]
	s_add_i32 m0, s12, 0x2000
	s_nop 0
	global_load_lds_dwordx4 v[144:145], off
	v_lshl_add_u64 v[144:145], v[250:251], 0, s[24:25]
	s_mov_b32 m0, s82
	s_nop 0
	global_load_lds_dwordx4 v[144:145], off
	v_lshl_add_u64 v[144:145], v[208:209], 0, s[24:25]
	s_mov_b32 m0, s83
	s_nop 0
	global_load_lds_dwordx4 v[144:145], off
	s_waitcnt vmcnt(8)
	s_waitcnt lgkmcnt(0)
	s_barrier
	s_setprio 1
	v_mfma_f32_16x16x32_bf16 v[60:63], v[148:151], v[180:183], v[60:63]
	v_mfma_f32_16x16x32_bf16 v[56:59], v[156:159], v[180:183], v[56:59]
	v_mfma_f32_16x16x32_bf16 v[44:47], v[148:151], v[188:191], v[44:47]
	v_mfma_f32_16x16x32_bf16 v[40:43], v[156:159], v[188:191], v[40:43]
	v_mfma_f32_16x16x32_bf16 v[28:31], v[148:151], v[198:201], v[28:31]
	v_mfma_f32_16x16x32_bf16 v[24:27], v[156:159], v[198:201], v[24:27]
	v_mfma_f32_16x16x32_bf16 v[12:15], v[148:151], v[212:215], v[12:15]
	v_mfma_f32_16x16x32_bf16 v[8:11], v[156:159], v[212:215], v[8:11]
	v_mfma_f32_16x16x32_bf16 v[60:63], v[152:155], v[184:187], v[60:63]
	v_mfma_f32_16x16x32_bf16 v[56:59], v[160:163], v[184:187], v[56:59]
	v_mfma_f32_16x16x32_bf16 v[44:47], v[152:155], v[194:197], v[44:47]
	v_mfma_f32_16x16x32_bf16 v[40:43], v[160:163], v[194:197], v[40:43]
	v_mfma_f32_16x16x32_bf16 v[28:31], v[152:155], v[202:205], v[28:31]
	v_mfma_f32_16x16x32_bf16 v[24:27], v[160:163], v[202:205], v[24:27]
	v_mfma_f32_16x16x32_bf16 v[12:15], v[152:155], v[242:245], v[12:15]
	v_mfma_f32_16x16x32_bf16 v[8:11], v[160:163], v[242:245], v[8:11]
	v_mfma_f32_16x16x32_bf16 v[52:55], v[164:167], v[180:183], v[52:55]
	v_mfma_f32_16x16x32_bf16 v[48:51], v[172:175], v[180:183], v[48:51]
	v_mfma_f32_16x16x32_bf16 v[36:39], v[164:167], v[188:191], v[36:39]
	v_mfma_f32_16x16x32_bf16 v[32:35], v[172:175], v[188:191], v[32:35]
	v_mfma_f32_16x16x32_bf16 v[20:23], v[164:167], v[198:201], v[20:23]
	v_mfma_f32_16x16x32_bf16 v[16:19], v[172:175], v[198:201], v[16:19]
	v_mfma_f32_16x16x32_bf16 v[4:7], v[164:167], v[212:215], v[4:7]
	v_mfma_f32_16x16x32_bf16 v[0:3], v[172:175], v[212:215], v[0:3]
	v_mfma_f32_16x16x32_bf16 v[52:55], v[168:171], v[184:187], v[52:55]
	v_mfma_f32_16x16x32_bf16 v[48:51], v[176:179], v[184:187], v[48:51]
	v_mfma_f32_16x16x32_bf16 v[36:39], v[168:171], v[194:197], v[36:39]
	v_mfma_f32_16x16x32_bf16 v[32:35], v[176:179], v[194:197], v[32:35]
	v_mfma_f32_16x16x32_bf16 v[20:23], v[168:171], v[202:205], v[20:23]
	v_mfma_f32_16x16x32_bf16 v[16:19], v[176:179], v[202:205], v[16:19]
	v_mfma_f32_16x16x32_bf16 v[4:7], v[168:171], v[242:245], v[4:7]
	v_mfma_f32_16x16x32_bf16 v[0:3], v[176:179], v[242:245], v[0:3]
	s_setprio 0
	s_barrier
	s_add_u32 s28, s28, 0x100
	s_addc_u32 s29, s29, 0
	s_add_u32 s18, s18, 0x100
	s_addc_u32 s19, s19, 0
	s_cmp_ge_u32 s21, s84
	s_mov_b32 s20, s21
	s_cbranch_scc0 .LBB0_161
	s_and_b64 vcc, exec, s[50:51]
	s_cbranch_vccz .LBB0_164

.LBB0_188:
	s_add_i32 s21, s20, 2
	s_add_u32 s12, s28, 0x80
	s_addc_u32 s13, s29, 0
	s_add_i32 s36, 0, 0x10000
	s_cmp_eq_u32 s67, s20
	s_cselect_b32 s57, s5, s13
	s_cselect_b32 s56, s4, s12
	s_cselect_b32 s13, s55, s19
	s_cselect_b32 s12, s54, s18
	s_add_i32 s20, 0, 0x14000
	v_add_u32_e32 v154, s36, v139
	v_add_u32_e32 v170, s20, v139
	ds_read_b128 v[142:145], v154
	ds_read_b128 v[146:149], v154 offset:1024
	ds_read_b128 v[150:153], v154 offset:2048
	ds_read_b128 v[154:157], v154 offset:3072
	ds_read_b128 v[158:161], v170
	ds_read_b128 v[162:165], v170 offset:1024
	ds_read_b128 v[166:169], v170 offset:2048
	ds_read_b128 v[170:173], v170 offset:3072
	v_lshl_add_u64 v[190:191], s[28:29], 0, v[134:135]
	s_add_i32 m0, s68, 0xc000
	ds_read_b128 v[174:177], v141
	ds_read_b128 v[178:181], v141 offset:1024
	ds_read_b128 v[182:185], v141 offset:2048
	ds_read_b128 v[186:189], v141 offset:3072
	ds_read_b128 v[194:197], v141 offset:4096
	ds_read_b128 v[198:201], v141 offset:5120
	ds_read_b128 v[202:205], v141 offset:6144
	ds_read_b128 v[212:215], v141 offset:7168
	global_load_lds_dwordx4 v[190:191], off
	v_lshl_add_u64 v[190:191], s[28:29], 0, v[136:137]
	s_add_i32 m0, s68, 0xe000
	s_nop 0
	global_load_lds_dwordx4 v[190:191], off
	s_waitcnt vmcnt(8)
	s_waitcnt lgkmcnt(0)
	s_barrier
	s_setprio 1
	v_mfma_f32_16x16x32_bf16 v[124:127], v[142:145], v[174:177], v[124:127]
	v_mfma_f32_16x16x32_bf16 v[120:123], v[150:153], v[174:177], v[120:123]
	v_mfma_f32_16x16x32_bf16 v[108:111], v[142:145], v[182:185], v[108:111]
	v_mfma_f32_16x16x32_bf16 v[104:107], v[150:153], v[182:185], v[104:107]
	v_mfma_f32_16x16x32_bf16 v[92:95], v[142:145], v[194:197], v[92:95]
	v_mfma_f32_16x16x32_bf16 v[88:91], v[150:153], v[194:197], v[88:91]
	v_mfma_f32_16x16x32_bf16 v[76:79], v[142:145], v[202:205], v[76:79]
	v_mfma_f32_16x16x32_bf16 v[72:75], v[150:153], v[202:205], v[72:75]
	v_mfma_f32_16x16x32_bf16 v[124:127], v[146:149], v[178:181], v[124:127]
	v_mfma_f32_16x16x32_bf16 v[120:123], v[154:157], v[178:181], v[120:123]
	v_mfma_f32_16x16x32_bf16 v[108:111], v[146:149], v[186:189], v[108:111]
	v_mfma_f32_16x16x32_bf16 v[104:107], v[154:157], v[186:189], v[104:107]
	v_mfma_f32_16x16x32_bf16 v[92:95], v[146:149], v[198:201], v[92:95]
	v_mfma_f32_16x16x32_bf16 v[88:91], v[154:157], v[198:201], v[88:91]
	v_mfma_f32_16x16x32_bf16 v[76:79], v[146:149], v[212:215], v[76:79]
	v_mfma_f32_16x16x32_bf16 v[72:75], v[154:157], v[212:215], v[72:75]
	v_mfma_f32_16x16x32_bf16 v[116:119], v[158:161], v[174:177], v[116:119]
	v_mfma_f32_16x16x32_bf16 v[112:115], v[166:169], v[174:177], v[112:115]
	v_mfma_f32_16x16x32_bf16 v[100:103], v[158:161], v[182:185], v[100:103]
	v_mfma_f32_16x16x32_bf16 v[96:99], v[166:169], v[182:185], v[96:99]
	v_mfma_f32_16x16x32_bf16 v[84:87], v[158:161], v[194:197], v[84:87]
	v_mfma_f32_16x16x32_bf16 v[80:83], v[166:169], v[194:197], v[80:83]
	v_mfma_f32_16x16x32_bf16 v[68:71], v[158:161], v[202:205], v[68:71]
	v_mfma_f32_16x16x32_bf16 v[64:67], v[166:169], v[202:205], v[64:67]
	v_mfma_f32_16x16x32_bf16 v[116:119], v[162:165], v[178:181], v[116:119]
	v_mfma_f32_16x16x32_bf16 v[112:115], v[170:173], v[178:181], v[112:115]
	v_mfma_f32_16x16x32_bf16 v[100:103], v[162:165], v[186:189], v[100:103]
	v_mfma_f32_16x16x32_bf16 v[96:99], v[170:173], v[186:189], v[96:99]
	v_mfma_f32_16x16x32_bf16 v[84:87], v[162:165], v[198:201], v[84:87]
	v_mfma_f32_16x16x32_bf16 v[80:83], v[170:173], v[198:201], v[80:83]
	v_mfma_f32_16x16x32_bf16 v[68:71], v[162:165], v[212:215], v[68:71]
	v_mfma_f32_16x16x32_bf16 v[64:67], v[170:173], v[212:215], v[64:67]
	s_setprio 0
	s_barrier
	s_add_i32 s36, s36, s70
	v_lshl_add_u64 v[190:191], s[12:13], 0, v[192:193]
	s_mov_b32 m0, s36
	ds_read_b128 v[174:177], v141 offset:16384
	ds_read_b128 v[178:181], v141 offset:17408
	ds_read_b128 v[182:185], v141 offset:18432
	ds_read_b128 v[186:189], v141 offset:19456
	ds_read_b128 v[194:197], v141 offset:20480
	ds_read_b128 v[198:201], v141 offset:21504
	ds_read_b128 v[202:205], v141 offset:22528
	ds_read_b128 v[212:215], v141 offset:23552
	global_load_lds_dwordx4 v[190:191], off
	s_add_i32 m0, s36, 0x2000
	v_lshl_add_u64 v[206:207], s[12:13], 0, v[128:129]
	s_add_u32 s12, s12, s58
	s_addc_u32 s13, s13, 0
	s_add_i32 s20, s20, s70
	global_load_lds_dwordx4 v[206:207], off
	v_lshl_add_u64 v[242:243], s[12:13], 0, v[192:193]
	s_mov_b32 m0, s20
	v_lshl_add_u64 v[244:245], s[12:13], 0, v[128:129]
	global_load_lds_dwordx4 v[242:243], off
	s_add_i32 m0, s20, 0x2000
	v_lshl_add_u64 v[246:247], s[56:57], 0, v[132:133]
	global_load_lds_dwordx4 v[244:245], off
	s_mov_b32 m0, s68
	v_lshl_add_u64 v[248:249], s[56:57], 0, v[130:131]
	global_load_lds_dwordx4 v[246:247], off
	s_mov_b32 m0, s75
	s_nop 0
	global_load_lds_dwordx4 v[248:249], off
	s_waitcnt vmcnt(8)
	s_waitcnt lgkmcnt(0)
	s_barrier
	s_setprio 1
	v_mfma_f32_16x16x32_bf16 v[60:63], v[142:145], v[174:177], v[60:63]
	v_mfma_f32_16x16x32_bf16 v[56:59], v[150:153], v[174:177], v[56:59]
	v_mfma_f32_16x16x32_bf16 v[44:47], v[142:145], v[182:185], v[44:47]
	v_mfma_f32_16x16x32_bf16 v[40:43], v[150:153], v[182:185], v[40:43]
	v_mfma_f32_16x16x32_bf16 v[28:31], v[142:145], v[194:197], v[28:31]
	v_mfma_f32_16x16x32_bf16 v[24:27], v[150:153], v[194:197], v[24:27]
	v_mfma_f32_16x16x32_bf16 v[12:15], v[142:145], v[202:205], v[12:15]
	v_mfma_f32_16x16x32_bf16 v[8:11], v[150:153], v[202:205], v[8:11]
	v_mfma_f32_16x16x32_bf16 v[60:63], v[146:149], v[178:181], v[60:63]
	v_mfma_f32_16x16x32_bf16 v[56:59], v[154:157], v[178:181], v[56:59]
	v_mfma_f32_16x16x32_bf16 v[44:47], v[146:149], v[186:189], v[44:47]
	v_mfma_f32_16x16x32_bf16 v[40:43], v[154:157], v[186:189], v[40:43]
	v_mfma_f32_16x16x32_bf16 v[28:31], v[146:149], v[198:201], v[28:31]
	v_mfma_f32_16x16x32_bf16 v[24:27], v[154:157], v[198:201], v[24:27]
	v_mfma_f32_16x16x32_bf16 v[12:15], v[146:149], v[212:215], v[12:15]
	v_mfma_f32_16x16x32_bf16 v[8:11], v[154:157], v[212:215], v[8:11]
	v_mfma_f32_16x16x32_bf16 v[52:55], v[158:161], v[174:177], v[52:55]
	v_mfma_f32_16x16x32_bf16 v[48:51], v[166:169], v[174:177], v[48:51]
	v_mfma_f32_16x16x32_bf16 v[36:39], v[158:161], v[182:185], v[36:39]
	v_mfma_f32_16x16x32_bf16 v[32:35], v[166:169], v[182:185], v[32:35]
	v_mfma_f32_16x16x32_bf16 v[20:23], v[158:161], v[194:197], v[20:23]
	v_mfma_f32_16x16x32_bf16 v[16:19], v[166:169], v[194:197], v[16:19]
	v_mfma_f32_16x16x32_bf16 v[4:7], v[158:161], v[202:205], v[4:7]
	v_mfma_f32_16x16x32_bf16 v[0:3], v[166:169], v[202:205], v[0:3]
	v_mfma_f32_16x16x32_bf16 v[52:55], v[162:165], v[178:181], v[52:55]
	v_mfma_f32_16x16x32_bf16 v[48:51], v[170:173], v[178:181], v[48:51]
	v_mfma_f32_16x16x32_bf16 v[36:39], v[162:165], v[186:189], v[36:39]
	v_mfma_f32_16x16x32_bf16 v[32:35], v[170:173], v[186:189], v[32:35]
	v_mfma_f32_16x16x32_bf16 v[20:23], v[162:165], v[198:201], v[20:23]
	v_mfma_f32_16x16x32_bf16 v[16:19], v[170:173], v[198:201], v[16:19]
	v_mfma_f32_16x16x32_bf16 v[4:7], v[162:165], v[212:215], v[4:7]
	v_mfma_f32_16x16x32_bf16 v[0:3], v[170:173], v[212:215], v[0:3]
	s_setprio 0
	s_barrier
	s_add_i32 s20, 0, 0x18000
	s_add_i32 s36, 0, 0x1c000
	v_add_u32_e32 v154, s20, v139
	v_add_u32_e32 v170, s36, v139
	ds_read_b128 v[142:145], v154
	ds_read_b128 v[146:149], v154 offset:1024
	ds_read_b128 v[150:153], v154 offset:2048
	ds_read_b128 v[154:157], v154 offset:3072
	ds_read_b128 v[158:161], v170
	ds_read_b128 v[162:165], v170 offset:1024
	ds_read_b128 v[166:169], v170 offset:2048
	ds_read_b128 v[170:173], v170 offset:3072
	s_add_u32 s12, s56, s34
	s_addc_u32 s13, s57, 0
	s_mov_b32 m0, s76
	v_lshl_add_u64 v[250:251], s[12:13], 0, v[132:133]
	ds_read_b128 v[174:177], v141 offset:32768
	ds_read_b128 v[178:181], v141 offset:33792
	ds_read_b128 v[182:185], v141 offset:34816
	ds_read_b128 v[186:189], v141 offset:35840
	ds_read_b128 v[194:197], v141 offset:36864
	ds_read_b128 v[198:201], v141 offset:37888
	ds_read_b128 v[202:205], v141 offset:38912
	ds_read_b128 v[212:215], v141 offset:39936
	global_load_lds_dwordx4 v[250:251], off
	v_lshl_add_u64 v[250:251], s[12:13], 0, v[130:131]
	s_mov_b32 m0, s77
	s_nop 0
	global_load_lds_dwordx4 v[250:251], off
	s_waitcnt vmcnt(8)
	s_waitcnt lgkmcnt(0)
	s_barrier
	s_setprio 1
	v_mfma_f32_16x16x32_bf16 v[124:127], v[142:145], v[174:177], v[124:127]
	v_mfma_f32_16x16x32_bf16 v[120:123], v[150:153], v[174:177], v[120:123]
	v_mfma_f32_16x16x32_bf16 v[108:111], v[142:145], v[182:185], v[108:111]
	v_mfma_f32_16x16x32_bf16 v[104:107], v[150:153], v[182:185], v[104:107]
	v_mfma_f32_16x16x32_bf16 v[92:95], v[142:145], v[194:197], v[92:95]
	v_mfma_f32_16x16x32_bf16 v[88:91], v[150:153], v[194:197], v[88:91]
	v_mfma_f32_16x16x32_bf16 v[76:79], v[142:145], v[202:205], v[76:79]
	v_mfma_f32_16x16x32_bf16 v[72:75], v[150:153], v[202:205], v[72:75]
	v_mfma_f32_16x16x32_bf16 v[124:127], v[146:149], v[178:181], v[124:127]
	v_mfma_f32_16x16x32_bf16 v[120:123], v[154:157], v[178:181], v[120:123]
	v_mfma_f32_16x16x32_bf16 v[108:111], v[146:149], v[186:189], v[108:111]
	v_mfma_f32_16x16x32_bf16 v[104:107], v[154:157], v[186:189], v[104:107]
	v_mfma_f32_16x16x32_bf16 v[92:95], v[146:149], v[198:201], v[92:95]
	v_mfma_f32_16x16x32_bf16 v[88:91], v[154:157], v[198:201], v[88:91]
	v_mfma_f32_16x16x32_bf16 v[76:79], v[146:149], v[212:215], v[76:79]
	v_mfma_f32_16x16x32_bf16 v[72:75], v[154:157], v[212:215], v[72:75]
	v_mfma_f32_16x16x32_bf16 v[116:119], v[158:161], v[174:177], v[116:119]
	v_mfma_f32_16x16x32_bf16 v[112:115], v[166:169], v[174:177], v[112:115]
	v_mfma_f32_16x16x32_bf16 v[100:103], v[158:161], v[182:185], v[100:103]
	v_mfma_f32_16x16x32_bf16 v[96:99], v[166:169], v[182:185], v[96:99]
	v_mfma_f32_16x16x32_bf16 v[84:87], v[158:161], v[194:197], v[84:87]
	v_mfma_f32_16x16x32_bf16 v[80:83], v[166:169], v[194:197], v[80:83]
	v_mfma_f32_16x16x32_bf16 v[68:71], v[158:161], v[202:205], v[68:71]
	v_mfma_f32_16x16x32_bf16 v[64:67], v[166:169], v[202:205], v[64:67]
	v_mfma_f32_16x16x32_bf16 v[116:119], v[162:165], v[178:181], v[116:119]
	v_mfma_f32_16x16x32_bf16 v[112:115], v[170:173], v[178:181], v[112:115]
	v_mfma_f32_16x16x32_bf16 v[100:103], v[162:165], v[186:189], v[100:103]
	v_mfma_f32_16x16x32_bf16 v[96:99], v[170:173], v[186:189], v[96:99]
	v_mfma_f32_16x16x32_bf16 v[84:87], v[162:165], v[198:201], v[84:87]
	v_mfma_f32_16x16x32_bf16 v[80:83], v[170:173], v[198:201], v[80:83]
	v_mfma_f32_16x16x32_bf16 v[68:71], v[162:165], v[212:215], v[68:71]
	v_mfma_f32_16x16x32_bf16 v[64:67], v[170:173], v[212:215], v[64:67]
	s_setprio 0
	s_barrier
	s_add_i32 s12, s20, s70
	v_lshl_add_u64 v[190:191], v[190:191], 0, s[24:25]
	s_mov_b32 m0, s12
	ds_read_b128 v[174:177], v141 offset:49152
	ds_read_b128 v[178:181], v141 offset:50176
	ds_read_b128 v[182:185], v141 offset:51200
	ds_read_b128 v[186:189], v141 offset:52224
	ds_read_b128 v[194:197], v141 offset:53248
	ds_read_b128 v[198:201], v141 offset:54272
	ds_read_b128 v[202:205], v141 offset:55296
	ds_read_b128 v[212:215], v141 offset:56320
	global_load_lds_dwordx4 v[190:191], off
	v_lshl_add_u64 v[190:191], v[206:207], 0, s[24:25]
	s_add_i32 m0, s12, 0x2000
	s_add_i32 s12, s36, s70
	global_load_lds_dwordx4 v[190:191], off
	v_lshl_add_u64 v[190:191], v[242:243], 0, s[24:25]
	s_mov_b32 m0, s12
	s_nop 0
	global_load_lds_dwordx4 v[190:191], off
	v_lshl_add_u64 v[190:191], v[244:245], 0, s[24:25]
	s_add_i32 m0, s12, 0x2000
	s_nop 0
	global_load_lds_dwordx4 v[190:191], off
	v_lshl_add_u64 v[190:191], v[246:247], 0, s[24:25]
	s_mov_b32 m0, s78
	s_nop 0
	global_load_lds_dwordx4 v[190:191], off
	v_lshl_add_u64 v[190:191], v[248:249], 0, s[24:25]
	s_mov_b32 m0, s79
	s_nop 0
	global_load_lds_dwordx4 v[190:191], off
	s_waitcnt vmcnt(8)
	s_waitcnt lgkmcnt(0)
	s_barrier
	s_setprio 1
	v_mfma_f32_16x16x32_bf16 v[60:63], v[142:145], v[174:177], v[60:63]
	v_mfma_f32_16x16x32_bf16 v[56:59], v[150:153], v[174:177], v[56:59]
	v_mfma_f32_16x16x32_bf16 v[44:47], v[142:145], v[182:185], v[44:47]
	v_mfma_f32_16x16x32_bf16 v[40:43], v[150:153], v[182:185], v[40:43]
	v_mfma_f32_16x16x32_bf16 v[28:31], v[142:145], v[194:197], v[28:31]
	v_mfma_f32_16x16x32_bf16 v[24:27], v[150:153], v[194:197], v[24:27]
	v_mfma_f32_16x16x32_bf16 v[12:15], v[142:145], v[202:205], v[12:15]
	v_mfma_f32_16x16x32_bf16 v[8:11], v[150:153], v[202:205], v[8:11]
	v_mfma_f32_16x16x32_bf16 v[60:63], v[146:149], v[178:181], v[60:63]
	v_mfma_f32_16x16x32_bf16 v[56:59], v[154:157], v[178:181], v[56:59]
	v_mfma_f32_16x16x32_bf16 v[44:47], v[146:149], v[186:189], v[44:47]
	v_mfma_f32_16x16x32_bf16 v[40:43], v[154:157], v[186:189], v[40:43]
	v_mfma_f32_16x16x32_bf16 v[28:31], v[146:149], v[198:201], v[28:31]
	v_mfma_f32_16x16x32_bf16 v[24:27], v[154:157], v[198:201], v[24:27]
	v_mfma_f32_16x16x32_bf16 v[12:15], v[146:149], v[212:215], v[12:15]
	v_mfma_f32_16x16x32_bf16 v[8:11], v[154:157], v[212:215], v[8:11]
	v_mfma_f32_16x16x32_bf16 v[52:55], v[158:161], v[174:177], v[52:55]
	v_mfma_f32_16x16x32_bf16 v[48:51], v[166:169], v[174:177], v[48:51]
	v_mfma_f32_16x16x32_bf16 v[36:39], v[158:161], v[182:185], v[36:39]
	v_mfma_f32_16x16x32_bf16 v[32:35], v[166:169], v[182:185], v[32:35]
	v_mfma_f32_16x16x32_bf16 v[20:23], v[158:161], v[194:197], v[20:23]
	v_mfma_f32_16x16x32_bf16 v[16:19], v[166:169], v[194:197], v[16:19]
	v_mfma_f32_16x16x32_bf16 v[4:7], v[158:161], v[202:205], v[4:7]
	v_mfma_f32_16x16x32_bf16 v[0:3], v[166:169], v[202:205], v[0:3]
	v_mfma_f32_16x16x32_bf16 v[52:55], v[162:165], v[178:181], v[52:55]
	v_mfma_f32_16x16x32_bf16 v[48:51], v[170:173], v[178:181], v[48:51]
	v_mfma_f32_16x16x32_bf16 v[36:39], v[162:165], v[186:189], v[36:39]
	v_mfma_f32_16x16x32_bf16 v[32:35], v[170:173], v[186:189], v[32:35]
	v_mfma_f32_16x16x32_bf16 v[20:23], v[162:165], v[198:201], v[20:23]
	v_mfma_f32_16x16x32_bf16 v[16:19], v[170:173], v[198:201], v[16:19]
	v_mfma_f32_16x16x32_bf16 v[4:7], v[162:165], v[212:215], v[4:7]
	v_mfma_f32_16x16x32_bf16 v[0:3], v[170:173], v[212:215], v[0:3]
	s_setprio 0
	s_barrier
	s_add_u32 s28, s28, 0x100
	s_addc_u32 s29, s29, 0
	s_add_u32 s18, s18, 0x100
	s_addc_u32 s19, s19, 0
	s_cmp_ge_u32 s21, s80
	s_mov_b32 s20, s21
	s_cbranch_scc0 .LBB0_188
	s_and_b64 vcc, exec, s[48:49]
	s_cbranch_vccz .LBB0_191
